# all six K=1024 GEMM inner loops hand-scheduled (in-place accumulators, fragment prefetch, counted waits)
# speedup vs baseline: 1.0163x; 1.0071x over previous
; DEV unsigned pack2(float a, float b) { f32x2 v = {a, b}; return __builtin_bit_cast(unsigned, __builtin_convertvector(v, bf2_t)); }
; template <class Epi>
; DEV void gemm_tile(const bf16_t* __restrict__ A, int lda, const bf16_t* __restrict__ Bt, int ldb, int K, int m0, int n0,
;                    Epi& epi, char* smem) {
;     ...
; #pragma unroll
;   for (int i = 0; i < 4; i++)
; #pragma unroll
;     for (int j = 0; j < 4; j++) epi(m0 + wm * 64 + j * 16 + l15, n0 + wn * 64 + i * 16 + quad * 4, acc[i][j]);
;   DEV void operator()(int m, int n, f32x4 v) {
;     uint2 r; r.x = pack2(v[0], v[1]); r.y = pack2(v[2], v[3]);
;     *(uint2*)(C + (size_t)m * ldc + n) = r;
;   }
.LBB0_177:
	s_nop 7
	s_nop 7
	v_and_or_b32 v0, v145, 15, s3
	v_add_u32_e32 v2, v0, v146
	v_lshrrev_b32_e32 v0, 2, v145
	v_and_b32_e32 v0, 12, v0
	v_or3_b32 v4, s2, v0, v144
	v_ashrrev_i32_e32 v5, 31, v4
	v_ashrrev_i32_e32 v3, 31, v2
	v_lshl_add_u64 v[4:5], v[4:5], 1, s[6:7]
	s_waitcnt vmcnt(7)
	v_lshlrev_b64 v[8:9], 12, v[2:3]
	v_cvt_pk_bf16_f32 v6, v106, v107
	v_cvt_pk_bf16_f32 v7, v108, v109
	v_lshl_add_u64 v[8:9], v[4:5], 0, v[8:9]
	global_store_dwordx2 v[8:9], v[6:7], off
	v_or_b32_e32 v6, 16, v2
	v_ashrrev_i32_e32 v7, 31, v6
	v_lshlrev_b64 v[6:7], 12, v[6:7]
	v_cvt_pk_bf16_f32 v10, v122, v123
	v_cvt_pk_bf16_f32 v11, v124, v125
	v_lshl_add_u64 v[6:7], v[4:5], 0, v[6:7]
	global_store_dwordx2 v[6:7], v[10:11], off
	v_or_b32_e32 v10, 32, v2
	v_or_b32_e32 v2, 48, v2
	v_ashrrev_i32_e32 v11, 31, v10
	v_ashrrev_i32_e32 v3, 31, v2
	v_lshlrev_b64 v[10:11], 12, v[10:11]
	v_lshlrev_b64 v[2:3], 12, v[2:3]
	v_lshl_add_u64 v[10:11], v[4:5], 0, v[10:11]
	v_lshl_add_u64 v[2:3], v[4:5], 0, v[2:3]
	v_cvt_pk_bf16_f32 v4, v102, v103
	v_cvt_pk_bf16_f32 v5, v104, v105
	global_store_dwordx2 v[8:9], v[4:5], off offset:32
	v_cvt_pk_bf16_f32 v4, v94, v95
	v_cvt_pk_bf16_f32 v5, v96, v97
	global_store_dwordx2 v[6:7], v[4:5], off offset:32
	v_cvt_pk_bf16_f32 v4, v86, v87
	v_cvt_pk_bf16_f32 v5, v88, v89
	global_store_dwordx2 v[10:11], v[4:5], off offset:32
	v_cvt_pk_bf16_f32 v4, v78, v79
	v_cvt_pk_bf16_f32 v5, v80, v81
	global_store_dwordx2 v[2:3], v[4:5], off offset:32
	v_cvt_pk_bf16_f32 v4, v82, v83
	v_cvt_pk_bf16_f32 v5, v84, v85
	global_store_dwordx2 v[8:9], v[4:5], off offset:64
	v_cvt_pk_bf16_f32 v4, v74, v75
	v_cvt_pk_bf16_f32 v5, v76, v77
	global_store_dwordx2 v[6:7], v[4:5], off offset:64
	v_cvt_pk_bf16_f32 v4, v70, v71
	v_cvt_pk_bf16_f32 v5, v72, v73
	global_store_dwordx2 v[10:11], v[4:5], off offset:64
	v_cvt_pk_bf16_f32 v4, v66, v67
	v_cvt_pk_bf16_f32 v5, v68, v69
	global_store_dwordx2 v[2:3], v[4:5], off offset:64
	v_cvt_pk_bf16_f32 v4, v98, v99
	v_cvt_pk_bf16_f32 v5, v100, v101
	global_store_dwordx2 v[8:9], v[4:5], off offset:96
	v_cvt_pk_bf16_f32 v4, v90, v91
	v_cvt_pk_bf16_f32 v5, v92, v93
	v_cvt_pk_bf16_f32 v12, v114, v115
	v_cvt_pk_bf16_f32 v13, v116, v117
	global_store_dwordx2 v[6:7], v[4:5], off offset:96
	v_cvt_pk_bf16_f32 v4, v126, v127
	v_cvt_pk_bf16_f32 v5, v128, v129
	global_store_dwordx2 v[10:11], v[12:13], off
	v_cvt_pk_bf16_f32 v12, v110, v111
	v_cvt_pk_bf16_f32 v13, v112, v113
	global_store_dwordx2 v[10:11], v[4:5], off offset:96
	v_cvt_pk_bf16_f32 v4, v118, v119
	v_cvt_pk_bf16_f32 v5, v120, v121
	global_store_dwordx2 v[2:3], v[12:13], off
	global_store_dwordx2 v[2:3], v[4:5], off offset:96

; DEV f32x4 mfma16(bf16x8 a, bf16x8 b, f32x4 c) { return __builtin_amdgcn_mfma_f32_16x16x32_bf16(a, b, c, 0, 0, 0); }
; template <int TI, int TJ, int KS>
; DEV void mfma_lds(const bf16_t* Arows, int lda, const bf16_t* Brows, int ldb, int i0, int j0, f32x4 (&acc)[TI][TJ]) {
;     ...
;   for (int ks = 0; ks < KS; ks++) {
;     bf16x8 af[TI], bfr[TJ];
; #pragma unroll
;     for (int i = 0; i < TI; i++) af[i] = *(const bf16x8*)(Arows + (i0 + i * 16 + l15) * lda + ks * 32 + quad * 8);
; #pragma unroll
;     for (int j = 0; j < TJ; j++) bfr[j] = *(const bf16x8*)(Brows + (j0 + j * 16 + l15) * ldb + ks * 32 + quad * 8);
; #pragma unroll
;     for (int i = 0; i < TI; i++)
; #pragma unroll
;       for (int j = 0; j < TJ; j++) acc[i][j] = mfma16(af[i], bfr[j], acc[i][j]);
;   }
.LBB0_181:
	v_mov_b32_e32 v130, v195
	v_and_b32_e32 v135, 15, v130
	v_or_b32_e32 v131, v135, v144
	v_and_b32_e32 v148, 48, v130
	v_mul_u32_u24_e32 v130, 0x50, v131
	v_lshl_add_u32 v147, v130, 1, v148
	v_or_b32_e32 v135, v135, v146
	v_mad_u32_u24 v238, v135, s36, v148
	v_lshl_add_u64 v[136:137], v[136:137], 0, s[34:35]
	v_lshl_add_u64 v[138:139], v[138:139], 0, s[34:35]
	s_andn2_b64 vcc, exec, s[14:15]
	ds_read_b128 v[148:151], v147 offset:20480
	ds_read_b128 v[164:167], v238
	ds_read_b128 v[168:171], v238 offset:2560
	ds_read_b128 v[172:175], v238 offset:5120
	ds_read_b128 v[176:179], v238 offset:7680
	ds_read_b128 v[152:155], v147 offset:23040
	ds_read_b128 v[156:159], v147 offset:25600
	ds_read_b128 v[160:163], v147 offset:28160
	ds_read_b128 v[180:183], v238 offset:64
	ds_read_b128 v[184:187], v238 offset:2624
	s_waitcnt lgkmcnt(8)
	v_mfma_f32_16x16x32_bf16 v[106:109], v[148:151], v[164:167], v[106:109]
	s_waitcnt lgkmcnt(7)
	v_mfma_f32_16x16x32_bf16 v[122:125], v[148:151], v[168:171], v[122:125]
	s_waitcnt lgkmcnt(6)
	v_mfma_f32_16x16x32_bf16 v[114:117], v[148:151], v[172:175], v[114:117]
	s_waitcnt lgkmcnt(5)
	v_mfma_f32_16x16x32_bf16 v[110:113], v[148:151], v[176:179], v[110:113]
	ds_read_b128 v[148:151], v147 offset:20544
	s_waitcnt lgkmcnt(5)
	v_mfma_f32_16x16x32_bf16 v[102:105], v[152:155], v[164:167], v[102:105]
	v_mfma_f32_16x16x32_bf16 v[94:97], v[152:155], v[168:171], v[94:97]
	v_mfma_f32_16x16x32_bf16 v[86:89], v[152:155], v[172:175], v[86:89]
	v_mfma_f32_16x16x32_bf16 v[78:81], v[152:155], v[176:179], v[78:81]
	ds_read_b128 v[152:155], v147 offset:23104
	s_waitcnt lgkmcnt(5)
	v_mfma_f32_16x16x32_bf16 v[82:85], v[156:159], v[164:167], v[82:85]
	v_mfma_f32_16x16x32_bf16 v[74:77], v[156:159], v[168:171], v[74:77]
	v_mfma_f32_16x16x32_bf16 v[70:73], v[156:159], v[172:175], v[70:73]
	v_mfma_f32_16x16x32_bf16 v[66:69], v[156:159], v[176:179], v[66:69]
	ds_read_b128 v[156:159], v147 offset:25664
	s_waitcnt lgkmcnt(5)
	v_mfma_f32_16x16x32_bf16 v[126:129], v[160:163], v[172:175], v[126:129]
	v_mfma_f32_16x16x32_bf16 v[118:121], v[160:163], v[176:179], v[118:121]
	ds_read_b128 v[172:175], v238 offset:5184
	ds_read_b128 v[176:179], v238 offset:7744
	v_mfma_f32_16x16x32_bf16 v[98:101], v[160:163], v[164:167], v[98:101]
	v_mfma_f32_16x16x32_bf16 v[90:93], v[160:163], v[168:171], v[90:93]
	ds_read_b128 v[160:163], v147 offset:28224
	s_waitcnt lgkmcnt(5)
	v_mfma_f32_16x16x32_bf16 v[106:109], v[148:151], v[180:183], v[106:109]
	s_waitcnt lgkmcnt(4)
	v_mfma_f32_16x16x32_bf16 v[102:105], v[152:155], v[180:183], v[102:105]
	s_waitcnt lgkmcnt(3)
	v_mfma_f32_16x16x32_bf16 v[82:85], v[156:159], v[180:183], v[82:85]
	v_mfma_f32_16x16x32_bf16 v[122:125], v[148:151], v[184:187], v[122:125]
	v_mfma_f32_16x16x32_bf16 v[94:97], v[152:155], v[184:187], v[94:97]
	v_mfma_f32_16x16x32_bf16 v[74:77], v[156:159], v[184:187], v[74:77]
	s_waitcnt lgkmcnt(2)
	v_mfma_f32_16x16x32_bf16 v[114:117], v[148:151], v[172:175], v[114:117]
	v_mfma_f32_16x16x32_bf16 v[86:89], v[152:155], v[172:175], v[86:89]
	v_mfma_f32_16x16x32_bf16 v[70:73], v[156:159], v[172:175], v[70:73]
	s_waitcnt lgkmcnt(1)
	v_mfma_f32_16x16x32_bf16 v[110:113], v[148:151], v[176:179], v[110:113]
	v_mfma_f32_16x16x32_bf16 v[78:81], v[152:155], v[176:179], v[78:81]
	v_mfma_f32_16x16x32_bf16 v[66:69], v[156:159], v[176:179], v[66:69]
	s_waitcnt lgkmcnt(0)
	v_mfma_f32_16x16x32_bf16 v[98:101], v[160:163], v[180:183], v[98:101]
	v_mfma_f32_16x16x32_bf16 v[90:93], v[160:163], v[184:187], v[90:93]
	v_mfma_f32_16x16x32_bf16 v[126:129], v[160:163], v[172:175], v[126:129]
	v_mfma_f32_16x16x32_bf16 v[118:121], v[160:163], v[176:179], v[118:121]
	s_cbranch_vccz .LBB0_177

; DEV f32x4 mfma16(bf16x8 a, bf16x8 b, f32x4 c) { return __builtin_amdgcn_mfma_f32_16x16x32_bf16(a, b, c, 0, 0, 0); }
; #define G_LOAD(RA, RB, KT) { _Pragma("unroll") for (int i = 0; i < 4; i++) { \
;       RA[i] = *(const u32x4*)(Ap + (size_t)(i * 32) * lda + (KT) * 64); RB[i] = *(const u32x4*)(Bp + (size_t)(i * 32) * ldb + (KT) * 64); } }
; #define G_STORE(RA, RB) { _Pragma("unroll") for (int i = 0; i < 4; i++) { \
;       *(u32x4*)(As + (lrow + i * 32) * GLD + lcc * 8) = RA[i]; *(u32x4*)(Bs + (lrow + i * 32) * GLD + lcc * 8) = RB[i]; } }
; template <int TI, int TJ, int KS>
; DEV void mfma_lds(const bf16_t* Arows, int lda, const bf16_t* Brows, int ldb, int i0, int j0, f32x4 (&acc)[TI][TJ]) {
;     ...
;   for (int ks = 0; ks < KS; ks++) {
;     bf16x8 af[TI], bfr[TJ];
; #pragma unroll
;     for (int i = 0; i < TI; i++) af[i] = *(const bf16x8*)(Arows + (i0 + i * 16 + l15) * lda + ks * 32 + quad * 8);
; #pragma unroll
;     for (int j = 0; j < TJ; j++) bfr[j] = *(const bf16x8*)(Brows + (j0 + j * 16 + l15) * ldb + ks * 32 + quad * 8);
; #pragma unroll
;     for (int i = 0; i < TI; i++)
; #pragma unroll
;       for (int j = 0; j < TJ; j++) acc[i][j] = mfma16(af[i], bfr[j], acc[i][j]);
;   }
; template <class Epi>
; DEV void gemm_tile(const bf16_t* __restrict__ A, int lda, const bf16_t* __restrict__ Bt, int ldb, int K, int m0, int n0,
;                    Epi& epi, char* smem) {
;     ...
;   for (int kt = 0; kt < nk; kt += 2) {
;     __syncthreads();
;     G_STORE(ra0, rb0);
;     __syncthreads();
;     if (kt + 2 < nk) G_LOAD(ra0, rb0, kt + 2);
;     mfma_lds<4, 4, 2>(Bs, GLD, As, GLD, wn * 64, wm * 64, acc);
;     __syncthreads();
;     G_STORE(ra1, rb1);
;     __syncthreads();
;     if (kt + 3 < nk) G_LOAD(ra1, rb1, kt + 3);
;     mfma_lds<4, 4, 2>(Bs, GLD, As, GLD, wn * 64, wm * 64, acc);
;   }
.LBB0_184:
	v_mov_b32_e32 v130, v195
	s_cmp_gt_u32 s12, 12
	v_and_b32_e32 v135, 15, v130
	v_or_b32_e32 v131, v135, v144
	v_and_b32_e32 v148, 48, v130
	v_mul_u32_u24_e32 v130, 0x50, v131
	v_lshl_add_u32 v147, v130, 1, v148
	v_or_b32_e32 v135, v135, v146
	v_mad_u32_u24 v238, v135, s36, v148
	ds_read_b128 v[148:151], v147 offset:20480
	ds_read_b128 v[164:167], v238
	ds_read_b128 v[168:171], v238 offset:2560
	ds_read_b128 v[172:175], v238 offset:5120
	ds_read_b128 v[176:179], v238 offset:7680
	ds_read_b128 v[152:155], v147 offset:23040
	ds_read_b128 v[156:159], v147 offset:25600
	ds_read_b128 v[160:163], v147 offset:28160
	ds_read_b128 v[180:183], v238 offset:64
	ds_read_b128 v[184:187], v238 offset:2624
	s_waitcnt lgkmcnt(8)
	v_mfma_f32_16x16x32_bf16 v[106:109], v[148:151], v[164:167], v[106:109]
	s_waitcnt lgkmcnt(7)
	v_mfma_f32_16x16x32_bf16 v[122:125], v[148:151], v[168:171], v[122:125]
	s_waitcnt lgkmcnt(6)
	v_mfma_f32_16x16x32_bf16 v[114:117], v[148:151], v[172:175], v[114:117]
	s_waitcnt lgkmcnt(5)
	v_mfma_f32_16x16x32_bf16 v[110:113], v[148:151], v[176:179], v[110:113]
	ds_read_b128 v[148:151], v147 offset:20544
	s_waitcnt lgkmcnt(5)
	v_mfma_f32_16x16x32_bf16 v[102:105], v[152:155], v[164:167], v[102:105]
	v_mfma_f32_16x16x32_bf16 v[94:97], v[152:155], v[168:171], v[94:97]
	v_mfma_f32_16x16x32_bf16 v[86:89], v[152:155], v[172:175], v[86:89]
	v_mfma_f32_16x16x32_bf16 v[78:81], v[152:155], v[176:179], v[78:81]
	ds_read_b128 v[152:155], v147 offset:23104
	s_waitcnt lgkmcnt(5)
	v_mfma_f32_16x16x32_bf16 v[82:85], v[156:159], v[164:167], v[82:85]
	v_mfma_f32_16x16x32_bf16 v[74:77], v[156:159], v[168:171], v[74:77]
	v_mfma_f32_16x16x32_bf16 v[70:73], v[156:159], v[172:175], v[70:73]
	v_mfma_f32_16x16x32_bf16 v[66:69], v[156:159], v[176:179], v[66:69]
	ds_read_b128 v[156:159], v147 offset:25664
	s_waitcnt lgkmcnt(5)
	v_mfma_f32_16x16x32_bf16 v[126:129], v[160:163], v[172:175], v[126:129]
	v_mfma_f32_16x16x32_bf16 v[118:121], v[160:163], v[176:179], v[118:121]
	ds_read_b128 v[172:175], v238 offset:5184
	ds_read_b128 v[176:179], v238 offset:7744
	v_mfma_f32_16x16x32_bf16 v[98:101], v[160:163], v[164:167], v[98:101]
	v_mfma_f32_16x16x32_bf16 v[90:93], v[160:163], v[168:171], v[90:93]
	ds_read_b128 v[160:163], v147 offset:28224
	s_waitcnt lgkmcnt(5)
	v_mfma_f32_16x16x32_bf16 v[106:109], v[148:151], v[180:183], v[106:109]
	s_waitcnt lgkmcnt(4)
	v_mfma_f32_16x16x32_bf16 v[102:105], v[152:155], v[180:183], v[102:105]
	s_waitcnt lgkmcnt(3)
	v_mfma_f32_16x16x32_bf16 v[82:85], v[156:159], v[180:183], v[82:85]
	v_mfma_f32_16x16x32_bf16 v[122:125], v[148:151], v[184:187], v[122:125]
	v_mfma_f32_16x16x32_bf16 v[94:97], v[152:155], v[184:187], v[94:97]
	v_mfma_f32_16x16x32_bf16 v[74:77], v[156:159], v[184:187], v[74:77]
	s_waitcnt lgkmcnt(2)
	v_mfma_f32_16x16x32_bf16 v[114:117], v[148:151], v[172:175], v[114:117]
	v_mfma_f32_16x16x32_bf16 v[86:89], v[152:155], v[172:175], v[86:89]
	v_mfma_f32_16x16x32_bf16 v[70:73], v[156:159], v[172:175], v[70:73]
	s_waitcnt lgkmcnt(1)
	v_mfma_f32_16x16x32_bf16 v[110:113], v[148:151], v[176:179], v[110:113]
	v_mfma_f32_16x16x32_bf16 v[78:81], v[152:155], v[176:179], v[78:81]
	v_mfma_f32_16x16x32_bf16 v[66:69], v[156:159], v[176:179], v[66:69]
	s_waitcnt lgkmcnt(0)
	v_mfma_f32_16x16x32_bf16 v[98:101], v[160:163], v[180:183], v[98:101]
	s_barrier
	v_mfma_f32_16x16x32_bf16 v[90:93], v[160:163], v[184:187], v[90:93]
	s_waitcnt vmcnt(8)
	ds_write_b128 v134, v[6:9]
	ds_write_b128 v134, v[14:17] offset:20480
	ds_write_b128 v134, v[22:25] offset:5120
	ds_write_b128 v134, v[30:33] offset:25600
	ds_write_b128 v134, v[38:41] offset:10240
	ds_write_b128 v134, v[46:49] offset:30720
	ds_write_b128 v134, v[54:57] offset:15360
	ds_write_b128 v134, v[62:65] offset:35840
	v_mfma_f32_16x16x32_bf16 v[126:129], v[160:163], v[172:175], v[126:129]
	s_waitcnt lgkmcnt(0)
	s_barrier
	v_mfma_f32_16x16x32_bf16 v[118:121], v[160:163], v[176:179], v[118:121]
	s_cbranch_scc1 .LBB0_181
	v_add_co_u32_e32 v6, vcc, 0x4200000, v142
	s_nop 1
	v_addc_co_u32_e32 v7, vcc, 0, v143, vcc
	v_add_co_u32_e32 v14, vcc, 0xba00000, v140
	global_load_dwordx4 v[6:9], v[6:7], off offset:384
	s_nop 0
	v_addc_co_u32_e32 v15, vcc, 0, v141, vcc
	v_add_co_u32_e32 v22, vcc, 0x4211000, v142
	global_load_dwordx4 v[14:17], v[14:15], off offset:384
	s_nop 0
	v_addc_co_u32_e32 v23, vcc, 0, v143, vcc
	v_add_co_u32_e32 v30, vcc, 0xba11000, v140
	global_load_dwordx4 v[22:25], v[22:23], off offset:384
	s_nop 0
	v_addc_co_u32_e32 v31, vcc, 0, v141, vcc
	v_add_co_u32_e32 v38, vcc, 0x4222000, v142
	global_load_dwordx4 v[30:33], v[30:31], off offset:384
	s_nop 0
	v_addc_co_u32_e32 v39, vcc, 0, v143, vcc
	v_add_co_u32_e32 v46, vcc, 0xba22000, v140
	global_load_dwordx4 v[38:41], v[38:39], off offset:384
	s_nop 0
	v_addc_co_u32_e32 v47, vcc, 0, v141, vcc
	v_add_co_u32_e32 v54, vcc, 0x4233000, v142
	global_load_dwordx4 v[46:49], v[46:47], off offset:384
	s_nop 0
	v_addc_co_u32_e32 v55, vcc, 0, v143, vcc
	v_add_co_u32_e32 v62, vcc, 0xba33000, v140
	global_load_dwordx4 v[54:57], v[54:55], off offset:384
	s_nop 0
	v_addc_co_u32_e32 v63, vcc, 0, v141, vcc
	global_load_dwordx4 v[62:65], v[62:63], off offset:384
	s_branch .LBB0_181

; DEV f32x4 mfma16(bf16x8 a, bf16x8 b, f32x4 c) { return __builtin_amdgcn_mfma_f32_16x16x32_bf16(a, b, c, 0, 0, 0); }
; template <int TI, int TJ, int KS>
; DEV void mfma_lds(const bf16_t* Arows, int lda, const bf16_t* Brows, int ldb, int i0, int j0, f32x4 (&acc)[TI][TJ]) {
;     ...
;   for (int ks = 0; ks < KS; ks++) {
;     bf16x8 af[TI], bfr[TJ];
; #pragma unroll
;     for (int i = 0; i < TI; i++) af[i] = *(const bf16x8*)(Arows + (i0 + i * 16 + l15) * lda + ks * 32 + quad * 8);
; #pragma unroll
;     for (int j = 0; j < TJ; j++) bfr[j] = *(const bf16x8*)(Brows + (j0 + j * 16 + l15) * ldb + ks * 32 + quad * 8);
; #pragma unroll
;     for (int i = 0; i < TI; i++)
; #pragma unroll
;       for (int j = 0; j < TJ; j++) acc[i][j] = mfma16(af[i], bfr[j], acc[i][j]);
;   }
.LBB0_200:
	v_mov_b32_e32 v131, v195
	v_and_b32_e32 v143, 15, v131
	v_or_b32_e32 v144, v143, v140
	v_and_b32_e32 v148, 48, v131
	v_mul_u32_u24_e32 v131, 0x50, v144
	v_lshl_add_u32 v131, v131, 1, v148
	v_or_b32_e32 v143, v143, v142
	v_mad_u32_u24 v238, v143, s36, v148
	v_lshl_add_u64 v[132:133], v[132:133], 0, s[34:35]
	v_lshl_add_u64 v[134:135], v[134:135], 0, s[34:35]
	s_and_b64 vcc, exec, s[16:17]
	ds_read_b128 v[144:147], v131 offset:20480
	ds_read_b128 v[160:163], v238
	ds_read_b128 v[164:167], v238 offset:2560
	ds_read_b128 v[168:171], v238 offset:5120
	ds_read_b128 v[172:175], v238 offset:7680
	ds_read_b128 v[148:151], v131 offset:23040
	ds_read_b128 v[152:155], v131 offset:25600
	ds_read_b128 v[156:159], v131 offset:28160
	ds_read_b128 v[176:179], v238 offset:64
	ds_read_b128 v[180:183], v238 offset:2624
	s_waitcnt lgkmcnt(8)
	v_mfma_f32_16x16x32_bf16 v[126:129], v[144:147], v[160:163], v[126:129]
	s_waitcnt lgkmcnt(7)
	v_mfma_f32_16x16x32_bf16 v[122:125], v[144:147], v[164:167], v[122:125]
	s_waitcnt lgkmcnt(6)
	v_mfma_f32_16x16x32_bf16 v[118:121], v[144:147], v[168:171], v[118:121]
	s_waitcnt lgkmcnt(5)
	v_mfma_f32_16x16x32_bf16 v[114:117], v[144:147], v[172:175], v[114:117]
	ds_read_b128 v[144:147], v131 offset:20544
	s_waitcnt lgkmcnt(5)
	v_mfma_f32_16x16x32_bf16 v[110:113], v[148:151], v[160:163], v[110:113]
	v_mfma_f32_16x16x32_bf16 v[74:77], v[148:151], v[164:167], v[74:77]
	v_mfma_f32_16x16x32_bf16 v[38:41], v[148:151], v[168:171], v[38:41]
	v_mfma_f32_16x16x32_bf16 v[34:37], v[148:151], v[172:175], v[34:37]
	ds_read_b128 v[148:151], v131 offset:23104
	s_waitcnt lgkmcnt(5)
	v_mfma_f32_16x16x32_bf16 v[30:33], v[152:155], v[160:163], v[30:33]
	v_mfma_f32_16x16x32_bf16 v[26:29], v[152:155], v[164:167], v[26:29]
	v_mfma_f32_16x16x32_bf16 v[22:25], v[152:155], v[168:171], v[22:25]
	v_mfma_f32_16x16x32_bf16 v[18:21], v[152:155], v[172:175], v[18:21]
	ds_read_b128 v[152:155], v131 offset:25664
	s_waitcnt lgkmcnt(5)
	v_mfma_f32_16x16x32_bf16 v[6:9], v[156:159], v[168:171], v[6:9]
	v_mfma_f32_16x16x32_bf16 v[2:5], v[156:159], v[172:175], v[2:5]
	ds_read_b128 v[168:171], v238 offset:5184
	ds_read_b128 v[172:175], v238 offset:7744
	v_mfma_f32_16x16x32_bf16 v[14:17], v[156:159], v[160:163], v[14:17]
	v_mfma_f32_16x16x32_bf16 v[10:13], v[156:159], v[164:167], v[10:13]
	ds_read_b128 v[156:159], v131 offset:28224
	s_waitcnt lgkmcnt(5)
	v_mfma_f32_16x16x32_bf16 v[126:129], v[144:147], v[176:179], v[126:129]
	s_waitcnt lgkmcnt(4)
	v_mfma_f32_16x16x32_bf16 v[110:113], v[148:151], v[176:179], v[110:113]
	s_waitcnt lgkmcnt(3)
	v_mfma_f32_16x16x32_bf16 v[30:33], v[152:155], v[176:179], v[30:33]
	v_mfma_f32_16x16x32_bf16 v[122:125], v[144:147], v[180:183], v[122:125]
	v_mfma_f32_16x16x32_bf16 v[74:77], v[148:151], v[180:183], v[74:77]
	v_mfma_f32_16x16x32_bf16 v[26:29], v[152:155], v[180:183], v[26:29]
	s_waitcnt lgkmcnt(2)
	v_mfma_f32_16x16x32_bf16 v[118:121], v[144:147], v[168:171], v[118:121]
	v_mfma_f32_16x16x32_bf16 v[38:41], v[148:151], v[168:171], v[38:41]
	v_mfma_f32_16x16x32_bf16 v[22:25], v[152:155], v[168:171], v[22:25]
	s_waitcnt lgkmcnt(1)
	v_mfma_f32_16x16x32_bf16 v[114:117], v[144:147], v[172:175], v[114:117]
	v_mfma_f32_16x16x32_bf16 v[34:37], v[148:151], v[172:175], v[34:37]
	v_mfma_f32_16x16x32_bf16 v[18:21], v[152:155], v[172:175], v[18:21]
	s_waitcnt lgkmcnt(0)
	v_mfma_f32_16x16x32_bf16 v[14:17], v[156:159], v[176:179], v[14:17]
	v_mfma_f32_16x16x32_bf16 v[10:13], v[156:159], v[180:183], v[10:13]
	v_mfma_f32_16x16x32_bf16 v[6:9], v[156:159], v[168:171], v[6:9]
	v_mfma_f32_16x16x32_bf16 v[2:5], v[156:159], v[172:175], v[2:5]
	s_cbranch_vccnz .LBB0_205

; DEV f32x4 mfma16(bf16x8 a, bf16x8 b, f32x4 c) { return __builtin_amdgcn_mfma_f32_16x16x32_bf16(a, b, c, 0, 0, 0); }
; #define G_LOAD(RA, RB, KT) { _Pragma("unroll") for (int i = 0; i < 4; i++) { \
;       RA[i] = *(const u32x4*)(Ap + (size_t)(i * 32) * lda + (KT) * 64); RB[i] = *(const u32x4*)(Bp + (size_t)(i * 32) * ldb + (KT) * 64); } }
; #define G_STORE(RA, RB) { _Pragma("unroll") for (int i = 0; i < 4; i++) { \
;       *(u32x4*)(As + (lrow + i * 32) * GLD + lcc * 8) = RA[i]; *(u32x4*)(Bs + (lrow + i * 32) * GLD + lcc * 8) = RB[i]; } }
; template <int TI, int TJ, int KS>
; DEV void mfma_lds(const bf16_t* Arows, int lda, const bf16_t* Brows, int ldb, int i0, int j0, f32x4 (&acc)[TI][TJ]) {
;     ...
;   for (int ks = 0; ks < KS; ks++) {
;     bf16x8 af[TI], bfr[TJ];
; #pragma unroll
;     for (int i = 0; i < TI; i++) af[i] = *(const bf16x8*)(Arows + (i0 + i * 16 + l15) * lda + ks * 32 + quad * 8);
; #pragma unroll
;     for (int j = 0; j < TJ; j++) bfr[j] = *(const bf16x8*)(Brows + (j0 + j * 16 + l15) * ldb + ks * 32 + quad * 8);
; #pragma unroll
;     for (int i = 0; i < TI; i++)
; #pragma unroll
;       for (int j = 0; j < TJ; j++) acc[i][j] = mfma16(af[i], bfr[j], acc[i][j]);
;   }
; template <class Epi>
; DEV void gemm_tile(const bf16_t* __restrict__ A, int lda, const bf16_t* __restrict__ Bt, int ldb, int K, int m0, int n0,
;                    Epi& epi, char* smem) {
;     ...
;   for (int kt = 0; kt < nk; kt += 2) {
;     __syncthreads();
;     G_STORE(ra0, rb0);
;     __syncthreads();
;     if (kt + 2 < nk) G_LOAD(ra0, rb0, kt + 2);
;     mfma_lds<4, 4, 2>(Bs, GLD, As, GLD, wn * 64, wm * 64, acc);
;     __syncthreads();
;     G_STORE(ra1, rb1);
;     __syncthreads();
;     if (kt + 3 < nk) G_LOAD(ra1, rb1, kt + 3);
;     mfma_lds<4, 4, 2>(Bs, GLD, As, GLD, wn * 64, wm * 64, acc);
;   }
.LBB0_203:
	v_mov_b32_e32 v131, v195
	s_cmp_gt_u32 s1, 12
	v_and_b32_e32 v143, 15, v131
	v_or_b32_e32 v144, v143, v140
	v_and_b32_e32 v148, 48, v131
	v_mul_u32_u24_e32 v131, 0x50, v144
	v_lshl_add_u32 v131, v131, 1, v148
	v_or_b32_e32 v143, v143, v142
	v_mad_u32_u24 v238, v143, s36, v148
	ds_read_b128 v[144:147], v131 offset:20480
	ds_read_b128 v[160:163], v238
	ds_read_b128 v[164:167], v238 offset:2560
	ds_read_b128 v[168:171], v238 offset:5120
	ds_read_b128 v[172:175], v238 offset:7680
	ds_read_b128 v[148:151], v131 offset:23040
	ds_read_b128 v[152:155], v131 offset:25600
	ds_read_b128 v[156:159], v131 offset:28160
	ds_read_b128 v[176:179], v238 offset:64
	ds_read_b128 v[180:183], v238 offset:2624
	s_waitcnt lgkmcnt(8)
	v_mfma_f32_16x16x32_bf16 v[126:129], v[144:147], v[160:163], v[126:129]
	s_waitcnt lgkmcnt(7)
	v_mfma_f32_16x16x32_bf16 v[122:125], v[144:147], v[164:167], v[122:125]
	s_waitcnt lgkmcnt(6)
	v_mfma_f32_16x16x32_bf16 v[118:121], v[144:147], v[168:171], v[118:121]
	s_waitcnt lgkmcnt(5)
	v_mfma_f32_16x16x32_bf16 v[114:117], v[144:147], v[172:175], v[114:117]
	ds_read_b128 v[144:147], v131 offset:20544
	s_waitcnt lgkmcnt(5)
	v_mfma_f32_16x16x32_bf16 v[110:113], v[148:151], v[160:163], v[110:113]
	v_mfma_f32_16x16x32_bf16 v[74:77], v[148:151], v[164:167], v[74:77]
	v_mfma_f32_16x16x32_bf16 v[38:41], v[148:151], v[168:171], v[38:41]
	v_mfma_f32_16x16x32_bf16 v[34:37], v[148:151], v[172:175], v[34:37]
	ds_read_b128 v[148:151], v131 offset:23104
	s_waitcnt lgkmcnt(5)
	v_mfma_f32_16x16x32_bf16 v[30:33], v[152:155], v[160:163], v[30:33]
	v_mfma_f32_16x16x32_bf16 v[26:29], v[152:155], v[164:167], v[26:29]
	v_mfma_f32_16x16x32_bf16 v[22:25], v[152:155], v[168:171], v[22:25]
	v_mfma_f32_16x16x32_bf16 v[18:21], v[152:155], v[172:175], v[18:21]
	ds_read_b128 v[152:155], v131 offset:25664
	s_waitcnt lgkmcnt(5)
	v_mfma_f32_16x16x32_bf16 v[6:9], v[156:159], v[168:171], v[6:9]
	v_mfma_f32_16x16x32_bf16 v[2:5], v[156:159], v[172:175], v[2:5]
	ds_read_b128 v[168:171], v238 offset:5184
	ds_read_b128 v[172:175], v238 offset:7744
	v_mfma_f32_16x16x32_bf16 v[14:17], v[156:159], v[160:163], v[14:17]
	v_mfma_f32_16x16x32_bf16 v[10:13], v[156:159], v[164:167], v[10:13]
	ds_read_b128 v[156:159], v131 offset:28224
	s_waitcnt lgkmcnt(5)
	v_mfma_f32_16x16x32_bf16 v[126:129], v[144:147], v[176:179], v[126:129]
	s_waitcnt lgkmcnt(4)
	v_mfma_f32_16x16x32_bf16 v[110:113], v[148:151], v[176:179], v[110:113]
	s_waitcnt lgkmcnt(3)
	v_mfma_f32_16x16x32_bf16 v[30:33], v[152:155], v[176:179], v[30:33]
	v_mfma_f32_16x16x32_bf16 v[122:125], v[144:147], v[180:183], v[122:125]
	v_mfma_f32_16x16x32_bf16 v[74:77], v[148:151], v[180:183], v[74:77]
	v_mfma_f32_16x16x32_bf16 v[26:29], v[152:155], v[180:183], v[26:29]
	s_waitcnt lgkmcnt(2)
	v_mfma_f32_16x16x32_bf16 v[118:121], v[144:147], v[168:171], v[118:121]
	v_mfma_f32_16x16x32_bf16 v[38:41], v[148:151], v[168:171], v[38:41]
	v_mfma_f32_16x16x32_bf16 v[22:25], v[152:155], v[168:171], v[22:25]
	s_waitcnt lgkmcnt(1)
	v_mfma_f32_16x16x32_bf16 v[114:117], v[144:147], v[172:175], v[114:117]
	v_mfma_f32_16x16x32_bf16 v[34:37], v[148:151], v[172:175], v[34:37]
	v_mfma_f32_16x16x32_bf16 v[18:21], v[152:155], v[172:175], v[18:21]
	s_waitcnt lgkmcnt(0)
	v_mfma_f32_16x16x32_bf16 v[14:17], v[156:159], v[176:179], v[14:17]
	s_barrier
	v_mfma_f32_16x16x32_bf16 v[10:13], v[156:159], v[180:183], v[10:13]
	s_waitcnt vmcnt(8)
	ds_write_b128 v130, v[46:49]
	ds_write_b128 v130, v[54:57] offset:20480
	ds_write_b128 v130, v[62:65] offset:5120
	ds_write_b128 v130, v[70:73] offset:25600
	ds_write_b128 v130, v[82:85] offset:10240
	ds_write_b128 v130, v[90:93] offset:30720
	ds_write_b128 v130, v[98:101] offset:15360
	ds_write_b128 v130, v[106:109] offset:35840
	v_mfma_f32_16x16x32_bf16 v[6:9], v[156:159], v[168:171], v[6:9]
	s_waitcnt lgkmcnt(0)
	s_barrier
	v_mfma_f32_16x16x32_bf16 v[2:5], v[156:159], v[172:175], v[2:5]
	s_cbranch_scc1 .LBB0_200
	v_add_co_u32_e32 v46, vcc, 0x4200000, v138
	s_nop 1
	v_addc_co_u32_e32 v47, vcc, 0, v139, vcc
	v_add_co_u32_e32 v54, vcc, 0xb3a0000, v136
	global_load_dwordx4 v[46:49], v[46:47], off offset:384
	s_nop 0
	v_addc_co_u32_e32 v55, vcc, 0, v137, vcc
	v_add_co_u32_e32 v62, vcc, 0x4211000, v138
	global_load_dwordx4 v[54:57], v[54:55], off offset:384
	s_nop 0
	v_addc_co_u32_e32 v63, vcc, 0, v139, vcc
	v_add_co_u32_e32 v70, vcc, 0xb3b1000, v136
	global_load_dwordx4 v[62:65], v[62:63], off offset:384
	s_nop 0
	v_addc_co_u32_e32 v71, vcc, 0, v137, vcc
	v_add_co_u32_e32 v82, vcc, 0x4222000, v138
	global_load_dwordx4 v[70:73], v[70:71], off offset:384
	s_nop 0
	v_addc_co_u32_e32 v83, vcc, 0, v139, vcc
	v_add_co_u32_e32 v90, vcc, 0xb3c2000, v136
	global_load_dwordx4 v[82:85], v[82:83], off offset:384
	s_nop 0
	v_addc_co_u32_e32 v91, vcc, 0, v137, vcc
	v_add_co_u32_e32 v98, vcc, 0x4233000, v138
	global_load_dwordx4 v[90:93], v[90:91], off offset:384
	s_nop 0
	v_addc_co_u32_e32 v99, vcc, 0, v139, vcc
	v_add_co_u32_e32 v106, vcc, 0xb3d3000, v136
	global_load_dwordx4 v[98:101], v[98:99], off offset:384
	s_nop 0
	v_addc_co_u32_e32 v107, vcc, 0, v137, vcc
	global_load_dwordx4 v[106:109], v[106:107], off offset:384
	s_branch .LBB0_200

; template <class Epi>
; DEV void gemm_tile(const bf16_t* __restrict__ A, int lda, const bf16_t* __restrict__ Bt, int ldb, int K, int m0, int n0,
;                    Epi& epi, char* smem) {
;     ...
; #pragma unroll
;   for (int i = 0; i < 4; i++)
; #pragma unroll
;     for (int j = 0; j < 4; j++) epi(m0 + wm * 64 + j * 16 + l15, n0 + wn * 64 + i * 16 + quad * 4, acc[i][j]);
;   DEV void operator()(int m, int n, f32x4 v) {
;     const float* src; int mr;
;     if (m < MM) { src = xin_main + (size_t)m * 1024 + n; mr = m >> 13; } else { src = xin_ctx + (size_t)(m - MM) * 1024 + n; mr = 2; }
;     float4 xo = *(const float4*)src;
;     float4 g = *(const float4*)(mod + (size_t)mr * 6144 + 2048 + n);
;     float4 r; r.x = xo.x + g.x * v[0]; r.y = xo.y + g.y * v[1]; r.z = xo.z + g.z * v[2]; r.w = xo.w + g.w * v[3];
;     *(float4*)(X + (size_t)m * 1024 + n) = r;
;   }
.LBB0_205:
	s_nop 7
	s_nop 7
	v_and_or_b32 v0, v141, 15, s0
	v_add_u32_e32 v44, v0, v142
	v_cmp_lt_i32_e64 s[38:39], s23, v44
	s_waitcnt vmcnt(7)
	v_add_u32_e32 v48, 0xffffc000, v44
	s_and_saveexec_b64 s[0:1], s[38:39]
	s_xor_b64 s[0:1], exec, s[0:1]
	v_mov_b32_e32 v49, v1
	v_lshlrev_b64 v[42:43], 12, v[48:49]
	v_mov_b32_e32 v45, v1
	v_lshl_add_u64 v[50:51], s[8:9], 0, v[42:43]
	v_lshlrev_b64 v[46:47], 12, v[44:45]
	s_or_saveexec_b64 s[0:1], s[0:1]
	v_ashrrev_i32_e32 v0, 13, v44
	v_mov_b64_e32 v[52:53], 0x3000
	v_ashrrev_i32_e32 v45, 31, v44
	v_mul_i32_i24_e32 v42, 0x1800, v0
	s_movk_i32 s19, 0x880
	s_xor_b64 exec, exec, s[0:1]
	v_lshlrev_b64 v[46:47], 12, v[44:45]
	v_ashrrev_i32_e32 v43, 31, v42
	v_lshl_add_u64 v[50:51], s[28:29], 0, v[46:47]
	v_mov_b64_e32 v[52:53], v[42:43]
	s_or_b64 exec, exec, s[0:1]
	v_lshrrev_b32_e32 v0, 2, v141
	v_and_b32_e32 v0, 12, v0
	v_or3_b32 v68, s13, v0, v140
	v_lshlrev_b32_e32 v0, 2, v68
	v_lshl_add_u64 v[52:53], v[52:53], 2, s[6:7]
	s_waitcnt vmcnt(6)
	v_lshl_add_u64 v[54:55], v[52:53], 0, v[0:1]
	v_add_co_u32_e32 v54, vcc, s21, v54
	v_lshl_add_u64 v[50:51], v[50:51], 0, v[0:1]
	s_nop 0
	v_addc_co_u32_e32 v55, vcc, 0, v55, vcc
	global_load_dwordx4 v[50:53], v[50:51], off
	v_lshl_add_u64 v[46:47], s[28:29], 0, v[46:47]
	global_load_dwordx4 v[54:57], v[54:55], off
	v_lshl_add_u64 v[46:47], v[46:47], 0, v[0:1]
	s_waitcnt vmcnt(0)
	v_pk_fma_f32 v[50:51], v[126:127], v[54:55], v[50:51]
	v_pk_fma_f32 v[52:53], v[128:129], v[56:57], v[52:53]
	global_store_dwordx4 v[46:47], v[50:53], off
	v_or_b32_e32 v46, 16, v44
	v_cmp_lt_i32_e64 s[40:41], s23, v46
	v_add_u32_e32 v52, 0xffffc010, v44
	s_and_saveexec_b64 s[0:1], s[40:41]
	s_xor_b64 s[0:1], exec, s[0:1]
	v_mov_b32_e32 v53, v1
	v_lshlrev_b64 v[50:51], 12, v[52:53]
	v_mov_b32_e32 v47, v1
	v_lshl_add_u64 v[54:55], s[8:9], 0, v[50:51]
	v_lshlrev_b64 v[50:51], 12, v[46:47]
	s_or_saveexec_b64 s[0:1], s[0:1]
	v_mov_b64_e32 v[56:57], 0x3000
	v_ashrrev_i32_e32 v47, 31, v46
	s_xor_b64 exec, exec, s[0:1]
	v_lshlrev_b64 v[50:51], 12, v[46:47]
	v_ashrrev_i32_e32 v43, 31, v42
	v_lshl_add_u64 v[54:55], s[28:29], 0, v[50:51]
	v_mov_b64_e32 v[56:57], v[42:43]
	s_or_b64 exec, exec, s[0:1]
	v_lshl_add_u64 v[56:57], v[56:57], 2, s[6:7]
	v_lshl_add_u64 v[58:59], v[56:57], 0, v[0:1]
	v_add_co_u32_e32 v58, vcc, s21, v58
	v_lshl_add_u64 v[54:55], v[54:55], 0, v[0:1]
	s_nop 0
	v_addc_co_u32_e32 v59, vcc, 0, v59, vcc
	global_load_dwordx4 v[54:57], v[54:55], off
	v_lshl_add_u64 v[50:51], s[28:29], 0, v[50:51]
	global_load_dwordx4 v[58:61], v[58:59], off
	v_lshl_add_u64 v[50:51], v[50:51], 0, v[0:1]
	s_waitcnt vmcnt(0)
	v_pk_fma_f32 v[54:55], v[122:123], v[58:59], v[54:55]
	v_pk_fma_f32 v[56:57], v[124:125], v[60:61], v[56:57]
	global_store_dwordx4 v[50:51], v[54:57], off
	v_or_b32_e32 v50, 32, v44
	v_cmp_lt_i32_e64 s[42:43], s23, v50
	v_add_u32_e32 v56, 0xffffc020, v44
	s_and_saveexec_b64 s[0:1], s[42:43]
	s_xor_b64 s[0:1], exec, s[0:1]
	v_mov_b32_e32 v57, v1
	v_lshlrev_b64 v[54:55], 12, v[56:57]
	v_mov_b32_e32 v51, v1
	v_lshl_add_u64 v[58:59], s[8:9], 0, v[54:55]
	v_lshlrev_b64 v[54:55], 12, v[50:51]
	s_or_saveexec_b64 s[0:1], s[0:1]
	v_mov_b64_e32 v[60:61], 0x3000
	v_ashrrev_i32_e32 v51, 31, v50
	s_xor_b64 exec, exec, s[0:1]
	v_lshlrev_b64 v[54:55], 12, v[50:51]
	v_ashrrev_i32_e32 v43, 31, v42
	v_lshl_add_u64 v[58:59], s[28:29], 0, v[54:55]
	v_mov_b64_e32 v[60:61], v[42:43]
	s_or_b64 exec, exec, s[0:1]
	v_lshl_add_u64 v[60:61], v[60:61], 2, s[6:7]
	v_lshl_add_u64 v[62:63], v[60:61], 0, v[0:1]
	v_add_co_u32_e32 v62, vcc, s21, v62
	v_lshl_add_u64 v[58:59], v[58:59], 0, v[0:1]
	s_nop 0
	v_addc_co_u32_e32 v63, vcc, 0, v63, vcc
	global_load_dwordx4 v[58:61], v[58:59], off
	v_lshl_add_u64 v[54:55], s[28:29], 0, v[54:55]
	global_load_dwordx4 v[62:65], v[62:63], off
	v_lshl_add_u64 v[54:55], v[54:55], 0, v[0:1]
	s_waitcnt vmcnt(0)
	v_pk_fma_f32 v[58:59], v[118:119], v[62:63], v[58:59]
	v_pk_fma_f32 v[60:61], v[120:121], v[64:65], v[60:61]
	global_store_dwordx4 v[54:55], v[58:61], off
	v_or_b32_e32 v54, 48, v44
	v_cmp_lt_i32_e64 s[44:45], s23, v54
	v_add_u32_e32 v58, 0xffffc030, v44
	s_and_saveexec_b64 s[0:1], s[44:45]
	s_xor_b64 s[0:1], exec, s[0:1]
	v_mov_b32_e32 v59, v1
	v_lshlrev_b64 v[60:61], 12, v[58:59]
	v_mov_b32_e32 v55, v1
	v_lshl_add_u64 v[62:63], s[8:9], 0, v[60:61]
	v_lshlrev_b64 v[60:61], 12, v[54:55]
	s_or_saveexec_b64 s[0:1], s[0:1]
	v_mov_b64_e32 v[64:65], 0x3000
	v_ashrrev_i32_e32 v55, 31, v54
	s_xor_b64 exec, exec, s[0:1]
	v_lshlrev_b64 v[60:61], 12, v[54:55]
	v_ashrrev_i32_e32 v43, 31, v42
	v_lshl_add_u64 v[62:63], s[28:29], 0, v[60:61]
	v_mov_b64_e32 v[64:65], v[42:43]
	s_or_b64 exec, exec, s[0:1]
	v_lshl_add_u64 v[64:65], v[64:65], 2, s[6:7]
	v_lshl_add_u64 v[66:67], v[64:65], 0, v[0:1]
	v_add_co_u32_e32 v66, vcc, s21, v66
	v_lshl_add_u64 v[62:63], v[62:63], 0, v[0:1]
	s_nop 0
	v_addc_co_u32_e32 v67, vcc, 0, v67, vcc
	global_load_dwordx4 v[62:65], v[62:63], off
	v_lshl_add_u64 v[60:61], s[28:29], 0, v[60:61]
	global_load_dwordx4 v[70:73], v[66:67], off
	v_lshl_add_u64 v[66:67], v[60:61], 0, v[0:1]
	s_waitcnt vmcnt(0)
; template <class Epi>
; DEV void gemm_tile(const bf16_t* __restrict__ A, int lda, const bf16_t* __restrict__ Bt, int ldb, int K, int m0, int n0,
;                    Epi& epi, char* smem) {
;     ...
; #pragma unroll
;   for (int i = 0; i < 4; i++)
; #pragma unroll
;     for (int j = 0; j < 4; j++) epi(m0 + wm * 64 + j * 16 + l15, n0 + wn * 64 + i * 16 + quad * 4, acc[i][j]);
;   DEV void operator()(int m, int n, f32x4 v) {
;     const float* src; int mr;
;     if (m < MM) { src = xin_main + (size_t)m * 1024 + n; mr = m >> 13; } else { src = xin_ctx + (size_t)(m - MM) * 1024 + n; mr = 2; }
;     float4 xo = *(const float4*)src;
;     float4 g = *(const float4*)(mod + (size_t)mr * 6144 + 2048 + n);
;     float4 r; r.x = xo.x + g.x * v[0]; r.y = xo.y + g.y * v[1]; r.z = xo.z + g.z * v[2]; r.w = xo.w + g.w * v[3];
;     *(float4*)(X + (size_t)m * 1024 + n) = r;
;   }
	v_pk_fma_f32 v[60:61], v[114:115], v[70:71], v[62:63]
	v_pk_fma_f32 v[62:63], v[116:117], v[72:73], v[64:65]
	global_store_dwordx4 v[66:67], v[60:63], off
	s_and_saveexec_b64 s[0:1], s[38:39]
	s_xor_b64 s[0:1], exec, s[0:1]
	v_mov_b32_e32 v49, v1
	v_lshlrev_b64 v[60:61], 12, v[48:49]
	v_mov_b32_e32 v62, v44
	v_mov_b32_e32 v63, v1
	v_lshl_add_u64 v[60:61], s[8:9], 0, v[60:61]
	v_lshlrev_b64 v[62:63], 12, v[62:63]
	s_or_saveexec_b64 s[0:1], s[0:1]
	v_mov_b64_e32 v[64:65], 0x3000
	s_xor_b64 exec, exec, s[0:1]
	v_lshlrev_b64 v[62:63], 12, v[44:45]
	v_ashrrev_i32_e32 v43, 31, v42
	v_lshl_add_u64 v[60:61], s[28:29], 0, v[62:63]
	v_mov_b64_e32 v[64:65], v[42:43]
	s_or_b64 exec, exec, s[0:1]
	v_or_b32_e32 v43, 16, v68
	v_lshl_add_u64 v[66:67], v[60:61], 0, v[0:1]
	v_lshl_add_u64 v[64:65], v[64:65], 2, s[6:7]
	v_lshlrev_b32_e32 v60, 2, v43
	v_mov_b32_e32 v61, v1
	v_lshl_add_u64 v[70:71], v[64:65], 0, v[60:61]
	v_add_co_u32_e32 v70, vcc, s21, v70
	global_load_dwordx4 v[64:67], v[66:67], off offset:64
	s_nop 0
	v_addc_co_u32_e32 v71, vcc, 0, v71, vcc
	global_load_dwordx4 v[70:73], v[70:71], off
	v_lshl_add_u64 v[62:63], s[28:29], 0, v[62:63]
	v_lshl_add_u64 v[78:79], v[62:63], 0, v[0:1]
	s_waitcnt vmcnt(0)
	v_pk_fma_f32 v[62:63], v[110:111], v[70:71], v[64:65]
	v_pk_fma_f32 v[64:65], v[112:113], v[72:73], v[66:67]
	global_store_dwordx4 v[78:79], v[62:65], off offset:64
	s_and_saveexec_b64 s[0:1], s[40:41]
	s_xor_b64 s[0:1], exec, s[0:1]
	v_mov_b32_e32 v53, v1
	v_lshlrev_b64 v[62:63], 12, v[52:53]
	v_lshl_add_u64 v[64:65], s[8:9], 0, v[62:63]
	v_mov_b32_e32 v62, v46
	v_mov_b32_e32 v63, v1
	v_lshlrev_b64 v[62:63], 12, v[62:63]
	s_or_saveexec_b64 s[0:1], s[0:1]
	v_mov_b64_e32 v[66:67], 0x3000
	s_xor_b64 exec, exec, s[0:1]
	v_lshlrev_b64 v[62:63], 12, v[46:47]
	v_ashrrev_i32_e32 v43, 31, v42
	v_lshl_add_u64 v[64:65], s[28:29], 0, v[62:63]
	v_mov_b64_e32 v[66:67], v[42:43]
	s_or_b64 exec, exec, s[0:1]
	v_lshl_add_u64 v[66:67], v[66:67], 2, s[6:7]
	v_mov_b32_e32 v61, v1
	v_lshl_add_u64 v[70:71], v[66:67], 0, v[60:61]
	v_add_co_u32_e32 v70, vcc, s21, v70
	v_lshl_add_u64 v[64:65], v[64:65], 0, v[0:1]
	s_nop 0
	v_addc_co_u32_e32 v71, vcc, 0, v71, vcc
	global_load_dwordx4 v[64:67], v[64:65], off offset:64
	v_lshl_add_u64 v[62:63], s[28:29], 0, v[62:63]
	global_load_dwordx4 v[70:73], v[70:71], off
	v_lshl_add_u64 v[78:79], v[62:63], 0, v[0:1]
	s_waitcnt vmcnt(0)
	v_pk_fma_f32 v[62:63], v[74:75], v[70:71], v[64:65]
	v_pk_fma_f32 v[64:65], v[76:77], v[72:73], v[66:67]
	global_store_dwordx4 v[78:79], v[62:65], off offset:64
	s_and_saveexec_b64 s[0:1], s[42:43]
	s_xor_b64 s[0:1], exec, s[0:1]
	v_mov_b32_e32 v57, v1
	v_lshlrev_b64 v[62:63], 12, v[56:57]
	v_lshl_add_u64 v[64:65], s[8:9], 0, v[62:63]
	v_mov_b32_e32 v62, v50
	v_mov_b32_e32 v63, v1
	v_lshlrev_b64 v[62:63], 12, v[62:63]
	s_or_saveexec_b64 s[0:1], s[0:1]
	v_mov_b64_e32 v[66:67], 0x3000
	s_xor_b64 exec, exec, s[0:1]
	v_lshlrev_b64 v[62:63], 12, v[50:51]
	v_ashrrev_i32_e32 v43, 31, v42
	v_lshl_add_u64 v[64:65], s[28:29], 0, v[62:63]
	v_mov_b64_e32 v[66:67], v[42:43]
	s_or_b64 exec, exec, s[0:1]
	v_lshl_add_u64 v[66:67], v[66:67], 2, s[6:7]
	v_mov_b32_e32 v61, v1
	v_lshl_add_u64 v[70:71], v[66:67], 0, v[60:61]
	v_add_co_u32_e32 v70, vcc, s21, v70
	v_lshl_add_u64 v[64:65], v[64:65], 0, v[0:1]
	s_nop 0
	v_addc_co_u32_e32 v71, vcc, 0, v71, vcc
	global_load_dwordx4 v[64:67], v[64:65], off offset:64
	v_lshl_add_u64 v[62:63], s[28:29], 0, v[62:63]
	global_load_dwordx4 v[70:73], v[70:71], off
	v_lshl_add_u64 v[62:63], v[62:63], 0, v[0:1]
	s_waitcnt vmcnt(0)
	v_pk_fma_f32 v[38:39], v[38:39], v[70:71], v[64:65]
	v_pk_fma_f32 v[40:41], v[40:41], v[72:73], v[66:67]
	global_store_dwordx4 v[62:63], v[38:41], off offset:64
	s_and_saveexec_b64 s[0:1], s[44:45]
	s_xor_b64 s[0:1], exec, s[0:1]
	v_mov_b32_e32 v59, v1
	v_lshlrev_b64 v[38:39], 12, v[58:59]
	v_lshl_add_u64 v[40:41], s[8:9], 0, v[38:39]
	v_mov_b32_e32 v38, v54
	v_mov_b32_e32 v39, v1
	v_lshlrev_b64 v[38:39], 12, v[38:39]
	s_or_saveexec_b64 s[0:1], s[0:1]
	v_mov_b64_e32 v[62:63], 0x3000
	s_xor_b64 exec, exec, s[0:1]
	v_lshlrev_b64 v[38:39], 12, v[54:55]
	v_ashrrev_i32_e32 v43, 31, v42
	v_lshl_add_u64 v[40:41], s[28:29], 0, v[38:39]
	v_mov_b64_e32 v[62:63], v[42:43]
	s_or_b64 exec, exec, s[0:1]
	v_lshl_add_u64 v[62:63], v[62:63], 2, s[6:7]
	v_mov_b32_e32 v61, v1
	v_lshl_add_u64 v[40:41], v[40:41], 0, v[0:1]
	v_lshl_add_u64 v[64:65], v[62:63], 0, v[60:61]
	global_load_dwordx4 v[60:63], v[40:41], off offset:64
	v_add_co_u32_e32 v40, vcc, s21, v64
	v_lshl_add_u64 v[38:39], s[28:29], 0, v[38:39]
	s_nop 0
	v_addc_co_u32_e32 v41, vcc, 0, v65, vcc
	global_load_dwordx4 v[64:67], v[40:41], off
	v_lshl_add_u64 v[38:39], v[38:39], 0, v[0:1]
	s_waitcnt vmcnt(0)
	v_pk_fma_f32 v[34:35], v[34:35], v[64:65], v[60:61]
	v_pk_fma_f32 v[36:37], v[36:37], v[66:67], v[62:63]
	global_store_dwordx4 v[38:39], v[34:37], off offset:64
	s_and_saveexec_b64 s[0:1], s[38:39]
	s_xor_b64 s[0:1], exec, s[0:1]
	v_mov_b32_e32 v49, v1
	v_lshlrev_b64 v[34:35], 12, v[48:49]
	v_mov_b32_e32 v36, v44
	v_mov_b32_e32 v37, v1
	v_lshl_add_u64 v[34:35], s[8:9], 0, v[34:35]
	v_lshlrev_b64 v[36:37], 12, v[36:37]
	s_or_saveexec_b64 s[0:1], s[0:1]
	v_mov_b64_e32 v[38:39], 0x3000
	s_xor_b64 exec, exec, s[0:1]
	v_lshlrev_b64 v[36:37], 12, v[44:45]
	v_ashrrev_i32_e32 v43, 31, v42
	v_lshl_add_u64 v[34:35], s[28:29], 0, v[36:37]
	v_mov_b64_e32 v[38:39], v[42:43]
	s_or_b64 exec, exec, s[0:1]
	v_or_b32_e32 v43, 32, v68
	v_lshl_add_u64 v[40:41], v[34:35], 0, v[0:1]
	v_lshl_add_u64 v[38:39], v[38:39], 2, s[6:7]
	v_lshlrev_b32_e32 v34, 2, v43
	v_mov_b32_e32 v35, v1
	v_lshl_add_u64 v[60:61], v[38:39], 0, v[34:35]
	v_add_co_u32_e32 v60, vcc, s21, v60
	global_load_dwordx4 v[38:41], v[40:41], off offset:128
	s_nop 0
	v_addc_co_u32_e32 v61, vcc, 0, v61, vcc
	global_load_dwordx4 v[60:63], v[60:61], off
	v_lshl_add_u64 v[36:37], s[28:29], 0, v[36:37]
	v_lshl_add_u64 v[36:37], v[36:37], 0, v[0:1]
	s_waitcnt vmcnt(0)
; template <class Epi>
; DEV void gemm_tile(const bf16_t* __restrict__ A, int lda, const bf16_t* __restrict__ Bt, int ldb, int K, int m0, int n0,
;                    Epi& epi, char* smem) {
;     ...
; #pragma unroll
;   for (int i = 0; i < 4; i++)
; #pragma unroll
;     for (int j = 0; j < 4; j++) epi(m0 + wm * 64 + j * 16 + l15, n0 + wn * 64 + i * 16 + quad * 4, acc[i][j]);
;   DEV void operator()(int m, int n, f32x4 v) {
;     const float* src; int mr;
;     if (m < MM) { src = xin_main + (size_t)m * 1024 + n; mr = m >> 13; } else { src = xin_ctx + (size_t)(m - MM) * 1024 + n; mr = 2; }
;     float4 xo = *(const float4*)src;
;     float4 g = *(const float4*)(mod + (size_t)mr * 6144 + 2048 + n);
;     float4 r; r.x = xo.x + g.x * v[0]; r.y = xo.y + g.y * v[1]; r.z = xo.z + g.z * v[2]; r.w = xo.w + g.w * v[3];
;     *(float4*)(X + (size_t)m * 1024 + n) = r;
;   }
	v_pk_fma_f32 v[30:31], v[30:31], v[60:61], v[38:39]
	v_pk_fma_f32 v[32:33], v[32:33], v[62:63], v[40:41]
	global_store_dwordx4 v[36:37], v[30:33], off offset:128
	s_and_saveexec_b64 s[0:1], s[40:41]
	s_xor_b64 s[0:1], exec, s[0:1]
	v_mov_b32_e32 v53, v1
	v_lshlrev_b64 v[30:31], 12, v[52:53]
	v_lshl_add_u64 v[32:33], s[8:9], 0, v[30:31]
	v_mov_b32_e32 v30, v46
	v_mov_b32_e32 v31, v1
	v_lshlrev_b64 v[30:31], 12, v[30:31]
	s_or_saveexec_b64 s[0:1], s[0:1]
	v_mov_b64_e32 v[36:37], 0x3000
	s_xor_b64 exec, exec, s[0:1]
	v_lshlrev_b64 v[30:31], 12, v[46:47]
	v_ashrrev_i32_e32 v43, 31, v42
	v_lshl_add_u64 v[32:33], s[28:29], 0, v[30:31]
	v_mov_b64_e32 v[36:37], v[42:43]
	s_or_b64 exec, exec, s[0:1]
	v_lshl_add_u64 v[36:37], v[36:37], 2, s[6:7]
	v_mov_b32_e32 v35, v1
	v_lshl_add_u64 v[32:33], v[32:33], 0, v[0:1]
	v_lshl_add_u64 v[40:41], v[36:37], 0, v[34:35]
	global_load_dwordx4 v[36:39], v[32:33], off offset:128
	v_add_co_u32_e32 v32, vcc, s21, v40
	v_lshl_add_u64 v[30:31], s[28:29], 0, v[30:31]
	s_nop 0
	v_addc_co_u32_e32 v33, vcc, 0, v41, vcc
	global_load_dwordx4 v[60:63], v[32:33], off
	v_lshl_add_u64 v[30:31], v[30:31], 0, v[0:1]
	s_waitcnt vmcnt(0)
	v_pk_fma_f32 v[26:27], v[26:27], v[60:61], v[36:37]
	v_pk_fma_f32 v[28:29], v[28:29], v[62:63], v[38:39]
	global_store_dwordx4 v[30:31], v[26:29], off offset:128
	s_and_saveexec_b64 s[0:1], s[42:43]
	s_xor_b64 s[0:1], exec, s[0:1]
	v_mov_b32_e32 v57, v1
	v_lshlrev_b64 v[26:27], 12, v[56:57]
	v_lshl_add_u64 v[28:29], s[8:9], 0, v[26:27]
	v_mov_b32_e32 v26, v50
	v_mov_b32_e32 v27, v1
	v_lshlrev_b64 v[26:27], 12, v[26:27]
	s_or_saveexec_b64 s[0:1], s[0:1]
	v_mov_b64_e32 v[30:31], 0x3000
	s_xor_b64 exec, exec, s[0:1]
	v_lshlrev_b64 v[26:27], 12, v[50:51]
	v_ashrrev_i32_e32 v43, 31, v42
	v_lshl_add_u64 v[28:29], s[28:29], 0, v[26:27]
	v_mov_b64_e32 v[30:31], v[42:43]
	s_or_b64 exec, exec, s[0:1]
	v_lshl_add_u64 v[30:31], v[30:31], 2, s[6:7]
	v_mov_b32_e32 v35, v1
	v_lshl_add_u64 v[32:33], v[30:31], 0, v[34:35]
	v_add_co_u32_e32 v32, vcc, s21, v32
	v_lshl_add_u64 v[28:29], v[28:29], 0, v[0:1]
	s_nop 0
	v_addc_co_u32_e32 v33, vcc, 0, v33, vcc
	global_load_dwordx4 v[28:31], v[28:29], off offset:128
	v_lshl_add_u64 v[26:27], s[28:29], 0, v[26:27]
	global_load_dwordx4 v[36:39], v[32:33], off
	v_lshl_add_u64 v[26:27], v[26:27], 0, v[0:1]
	s_waitcnt vmcnt(0)
	v_pk_fma_f32 v[22:23], v[22:23], v[36:37], v[28:29]
	v_pk_fma_f32 v[24:25], v[24:25], v[38:39], v[30:31]
	global_store_dwordx4 v[26:27], v[22:25], off offset:128
	s_and_saveexec_b64 s[0:1], s[44:45]
	s_xor_b64 s[0:1], exec, s[0:1]
	v_mov_b32_e32 v59, v1
	v_lshlrev_b64 v[22:23], 12, v[58:59]
	v_lshl_add_u64 v[24:25], s[8:9], 0, v[22:23]
	v_mov_b32_e32 v22, v54
	v_mov_b32_e32 v23, v1
	v_lshlrev_b64 v[22:23], 12, v[22:23]
	s_or_saveexec_b64 s[0:1], s[0:1]
	v_mov_b64_e32 v[26:27], 0x3000
	s_xor_b64 exec, exec, s[0:1]
	v_lshlrev_b64 v[22:23], 12, v[54:55]
	v_ashrrev_i32_e32 v43, 31, v42
	v_lshl_add_u64 v[24:25], s[28:29], 0, v[22:23]
	v_mov_b64_e32 v[26:27], v[42:43]
	s_or_b64 exec, exec, s[0:1]
	v_lshl_add_u64 v[26:27], v[26:27], 2, s[6:7]
	v_mov_b32_e32 v35, v1
	v_lshl_add_u64 v[28:29], v[26:27], 0, v[34:35]
	v_add_co_u32_e32 v28, vcc, s21, v28
	v_lshl_add_u64 v[24:25], v[24:25], 0, v[0:1]
	s_nop 0
	v_addc_co_u32_e32 v29, vcc, 0, v29, vcc
	global_load_dwordx4 v[24:27], v[24:25], off offset:128
	v_lshl_add_u64 v[22:23], s[28:29], 0, v[22:23]
	global_load_dwordx4 v[28:31], v[28:29], off
	v_lshl_add_u64 v[22:23], v[22:23], 0, v[0:1]
	s_waitcnt vmcnt(0)
; template <class Epi>
; DEV void gemm_tile(const bf16_t* __restrict__ A, int lda, const bf16_t* __restrict__ Bt, int ldb, int K, int m0, int n0,
;                    Epi& epi, char* smem) {
;     ...
; #pragma unroll
;   for (int i = 0; i < 4; i++)
; #pragma unroll
;     for (int j = 0; j < 4; j++) epi(m0 + wm * 64 + j * 16 + l15, n0 + wn * 64 + i * 16 + quad * 4, acc[i][j]);
;   DEV void operator()(int m, int n, f32x4 v) {
;     const float* src; int mr;
;     if (m < MM) { src = xin_main + (size_t)m * 1024 + n; mr = m >> 13; } else { src = xin_ctx + (size_t)(m - MM) * 1024 + n; mr = 2; }
;     float4 xo = *(const float4*)src;
;     float4 g = *(const float4*)(mod + (size_t)mr * 6144 + 2048 + n);
;     float4 r; r.x = xo.x + g.x * v[0]; r.y = xo.y + g.y * v[1]; r.z = xo.z + g.z * v[2]; r.w = xo.w + g.w * v[3];
;     *(float4*)(X + (size_t)m * 1024 + n) = r;
;   }
	v_pk_fma_f32 v[18:19], v[18:19], v[28:29], v[24:25]
	v_pk_fma_f32 v[20:21], v[20:21], v[30:31], v[26:27]
	global_store_dwordx4 v[22:23], v[18:21], off offset:128
	s_and_saveexec_b64 s[0:1], s[38:39]
	s_xor_b64 s[0:1], exec, s[0:1]
	v_mov_b32_e32 v49, v1
	v_lshlrev_b64 v[18:19], 12, v[48:49]
	v_mov_b32_e32 v45, v1
	v_lshl_add_u64 v[18:19], s[8:9], 0, v[18:19]
	v_lshlrev_b64 v[20:21], 12, v[44:45]
	s_or_saveexec_b64 s[0:1], s[0:1]
	v_mov_b64_e32 v[22:23], 0x3000
	s_xor_b64 exec, exec, s[0:1]
	v_lshlrev_b64 v[20:21], 12, v[44:45]
	v_ashrrev_i32_e32 v43, 31, v42
	v_lshl_add_u64 v[18:19], s[28:29], 0, v[20:21]
	v_mov_b64_e32 v[22:23], v[42:43]
	s_or_b64 exec, exec, s[0:1]
	v_or_b32_e32 v26, 48, v68
	v_lshl_add_u64 v[24:25], v[18:19], 0, v[0:1]
	v_lshl_add_u64 v[22:23], v[22:23], 2, s[6:7]
	v_lshlrev_b32_e32 v18, 2, v26
	v_mov_b32_e32 v19, v1
	v_lshl_add_u64 v[26:27], v[22:23], 0, v[18:19]
	v_add_co_u32_e32 v26, vcc, s21, v26
	global_load_dwordx4 v[22:25], v[24:25], off offset:192
	s_nop 0
	v_addc_co_u32_e32 v27, vcc, 0, v27, vcc
	global_load_dwordx4 v[26:29], v[26:27], off
	v_lshl_add_u64 v[20:21], s[28:29], 0, v[20:21]
	v_lshl_add_u64 v[20:21], v[20:21], 0, v[0:1]
	s_waitcnt vmcnt(0)
	v_pk_fma_f32 v[14:15], v[14:15], v[26:27], v[22:23]
	v_pk_fma_f32 v[16:17], v[16:17], v[28:29], v[24:25]
	global_store_dwordx4 v[20:21], v[14:17], off offset:192
	s_and_saveexec_b64 s[0:1], s[40:41]
	s_xor_b64 s[0:1], exec, s[0:1]
	v_mov_b32_e32 v53, v1
	v_lshlrev_b64 v[14:15], 12, v[52:53]
	v_mov_b32_e32 v47, v1
	v_lshl_add_u64 v[16:17], s[8:9], 0, v[14:15]
	v_lshlrev_b64 v[14:15], 12, v[46:47]
	s_or_saveexec_b64 s[0:1], s[0:1]
	v_mov_b64_e32 v[20:21], 0x3000
	s_xor_b64 exec, exec, s[0:1]
	v_lshlrev_b64 v[14:15], 12, v[46:47]
	v_ashrrev_i32_e32 v43, 31, v42
	v_lshl_add_u64 v[16:17], s[28:29], 0, v[14:15]
	v_mov_b64_e32 v[20:21], v[42:43]
	s_or_b64 exec, exec, s[0:1]
	v_lshl_add_u64 v[20:21], v[20:21], 2, s[6:7]
	v_mov_b32_e32 v19, v1
	v_lshl_add_u64 v[16:17], v[16:17], 0, v[0:1]
	v_lshl_add_u64 v[24:25], v[20:21], 0, v[18:19]
	global_load_dwordx4 v[20:23], v[16:17], off offset:192
	v_add_co_u32_e32 v16, vcc, s21, v24
	v_lshl_add_u64 v[14:15], s[28:29], 0, v[14:15]
	s_nop 0
	v_addc_co_u32_e32 v17, vcc, 0, v25, vcc
	global_load_dwordx4 v[24:27], v[16:17], off
	v_lshl_add_u64 v[14:15], v[14:15], 0, v[0:1]
	s_waitcnt vmcnt(0)
	v_pk_fma_f32 v[10:11], v[10:11], v[24:25], v[20:21]
	v_pk_fma_f32 v[12:13], v[12:13], v[26:27], v[22:23]
	global_store_dwordx4 v[14:15], v[10:13], off offset:192
	s_and_saveexec_b64 s[0:1], s[42:43]
	s_xor_b64 s[0:1], exec, s[0:1]
	v_mov_b32_e32 v57, v1
	v_lshlrev_b64 v[10:11], 12, v[56:57]
	v_mov_b32_e32 v51, v1
	v_lshl_add_u64 v[12:13], s[8:9], 0, v[10:11]
	v_lshlrev_b64 v[10:11], 12, v[50:51]
	s_or_saveexec_b64 s[0:1], s[0:1]
	v_mov_b64_e32 v[14:15], 0x3000
	s_xor_b64 exec, exec, s[0:1]
	v_lshlrev_b64 v[10:11], 12, v[50:51]
	v_ashrrev_i32_e32 v43, 31, v42
	v_lshl_add_u64 v[12:13], s[28:29], 0, v[10:11]
	v_mov_b64_e32 v[14:15], v[42:43]
	s_or_b64 exec, exec, s[0:1]
	v_lshl_add_u64 v[14:15], v[14:15], 2, s[6:7]
	v_mov_b32_e32 v19, v1
	v_lshl_add_u64 v[16:17], v[14:15], 0, v[18:19]
	v_add_co_u32_e32 v16, vcc, s21, v16
	v_lshl_add_u64 v[12:13], v[12:13], 0, v[0:1]
	s_nop 0
	v_addc_co_u32_e32 v17, vcc, 0, v17, vcc
	global_load_dwordx4 v[12:15], v[12:13], off offset:192
	v_lshl_add_u64 v[10:11], s[28:29], 0, v[10:11]
	global_load_dwordx4 v[20:23], v[16:17], off
	v_lshl_add_u64 v[10:11], v[10:11], 0, v[0:1]
	s_waitcnt vmcnt(0)
	v_pk_fma_f32 v[6:7], v[6:7], v[20:21], v[12:13]
	v_pk_fma_f32 v[8:9], v[8:9], v[22:23], v[14:15]
	global_store_dwordx4 v[10:11], v[6:9], off offset:192
	s_and_saveexec_b64 s[0:1], s[44:45]
	s_xor_b64 s[0:1], exec, s[0:1]
	v_mov_b32_e32 v59, v1
	v_lshlrev_b64 v[6:7], 12, v[58:59]
	v_mov_b32_e32 v55, v1
	v_lshl_add_u64 v[8:9], s[8:9], 0, v[6:7]
	v_lshlrev_b64 v[6:7], 12, v[54:55]
	s_or_saveexec_b64 s[0:1], s[0:1]
	v_mov_b64_e32 v[10:11], 0x3000
	s_xor_b64 exec, exec, s[0:1]
	s_cbranch_execz .LBB0_196
	v_lshlrev_b64 v[6:7], 12, v[54:55]
	v_ashrrev_i32_e32 v43, 31, v42
	v_lshl_add_u64 v[8:9], s[28:29], 0, v[6:7]
	v_mov_b64_e32 v[10:11], v[42:43]
	s_branch .LBB0_196

; DEV f32x4 mfma16(bf16x8 a, bf16x8 b, f32x4 c) { return __builtin_amdgcn_mfma_f32_16x16x32_bf16(a, b, c, 0, 0, 0); }
; template <int TI, int TJ, int KS>
; DEV void mfma_lds(const bf16_t* Arows, int lda, const bf16_t* Brows, int ldb, int i0, int j0, f32x4 (&acc)[TI][TJ]) {
;     ...
;   for (int ks = 0; ks < KS; ks++) {
;     bf16x8 af[TI], bfr[TJ];
; #pragma unroll
;     for (int i = 0; i < TI; i++) af[i] = *(const bf16x8*)(Arows + (i0 + i * 16 + l15) * lda + ks * 32 + quad * 8);
; #pragma unroll
;     for (int j = 0; j < TJ; j++) bfr[j] = *(const bf16x8*)(Brows + (j0 + j * 16 + l15) * ldb + ks * 32 + quad * 8);
; #pragma unroll
;     for (int i = 0; i < TI; i++)
; #pragma unroll
;       for (int j = 0; j < TJ; j++) acc[i][j] = mfma16(af[i], bfr[j], acc[i][j]);
;   }
.LBB0_324:
	v_mov_b32_e32 v131, v195
	v_and_b32_e32 v143, 15, v131
	v_or_b32_e32 v144, v143, v142
	v_and_b32_e32 v148, 48, v131
	v_mul_u32_u24_e32 v131, 0x50, v144
	v_lshl_add_u32 v131, v131, 1, v148
	v_or_b32_e32 v143, v143, v141
	v_mad_u32_u24 v238, v143, s36, v148
	v_lshl_add_u64 v[132:133], v[132:133], 0, s[34:35]
	v_lshl_add_u64 v[134:135], v[134:135], 0, s[34:35]
	s_and_b64 vcc, exec, s[6:7]
	ds_read_b128 v[144:147], v131 offset:20480
	ds_read_b128 v[160:163], v238
	ds_read_b128 v[164:167], v238 offset:2560
	ds_read_b128 v[168:171], v238 offset:5120
	ds_read_b128 v[172:175], v238 offset:7680
	ds_read_b128 v[148:151], v131 offset:23040
	ds_read_b128 v[152:155], v131 offset:25600
	ds_read_b128 v[156:159], v131 offset:28160
	ds_read_b128 v[176:179], v238 offset:64
	ds_read_b128 v[180:183], v238 offset:2624
	s_waitcnt lgkmcnt(8)
	v_mfma_f32_16x16x32_bf16 v[62:65], v[144:147], v[160:163], v[62:65]
	s_waitcnt lgkmcnt(7)
	v_mfma_f32_16x16x32_bf16 v[58:61], v[144:147], v[164:167], v[58:61]
	s_waitcnt lgkmcnt(6)
	v_mfma_f32_16x16x32_bf16 v[54:57], v[144:147], v[168:171], v[54:57]
	s_waitcnt lgkmcnt(5)
	v_mfma_f32_16x16x32_bf16 v[50:53], v[144:147], v[172:175], v[50:53]
	ds_read_b128 v[144:147], v131 offset:20544
	s_waitcnt lgkmcnt(5)
	v_mfma_f32_16x16x32_bf16 v[46:49], v[148:151], v[160:163], v[46:49]
	v_mfma_f32_16x16x32_bf16 v[42:45], v[148:151], v[164:167], v[42:45]
	v_mfma_f32_16x16x32_bf16 v[38:41], v[148:151], v[168:171], v[38:41]
	v_mfma_f32_16x16x32_bf16 v[34:37], v[148:151], v[172:175], v[34:37]
	ds_read_b128 v[148:151], v131 offset:23104
	s_waitcnt lgkmcnt(5)
	v_mfma_f32_16x16x32_bf16 v[30:33], v[152:155], v[160:163], v[30:33]
	v_mfma_f32_16x16x32_bf16 v[26:29], v[152:155], v[164:167], v[26:29]
	v_mfma_f32_16x16x32_bf16 v[22:25], v[152:155], v[168:171], v[22:25]
	v_mfma_f32_16x16x32_bf16 v[18:21], v[152:155], v[172:175], v[18:21]
	ds_read_b128 v[152:155], v131 offset:25664
	s_waitcnt lgkmcnt(5)
	v_mfma_f32_16x16x32_bf16 v[6:9], v[156:159], v[168:171], v[6:9]
	v_mfma_f32_16x16x32_bf16 v[2:5], v[156:159], v[172:175], v[2:5]
	ds_read_b128 v[168:171], v238 offset:5184
	ds_read_b128 v[172:175], v238 offset:7744
	v_mfma_f32_16x16x32_bf16 v[14:17], v[156:159], v[160:163], v[14:17]
	v_mfma_f32_16x16x32_bf16 v[10:13], v[156:159], v[164:167], v[10:13]
	ds_read_b128 v[156:159], v131 offset:28224
	s_waitcnt lgkmcnt(5)
	v_mfma_f32_16x16x32_bf16 v[62:65], v[144:147], v[176:179], v[62:65]
	s_waitcnt lgkmcnt(4)
	v_mfma_f32_16x16x32_bf16 v[46:49], v[148:151], v[176:179], v[46:49]
	s_waitcnt lgkmcnt(3)
	v_mfma_f32_16x16x32_bf16 v[30:33], v[152:155], v[176:179], v[30:33]
	v_mfma_f32_16x16x32_bf16 v[58:61], v[144:147], v[180:183], v[58:61]
	v_mfma_f32_16x16x32_bf16 v[42:45], v[148:151], v[180:183], v[42:45]
	v_mfma_f32_16x16x32_bf16 v[26:29], v[152:155], v[180:183], v[26:29]
	s_waitcnt lgkmcnt(2)
	v_mfma_f32_16x16x32_bf16 v[54:57], v[144:147], v[168:171], v[54:57]
	v_mfma_f32_16x16x32_bf16 v[38:41], v[148:151], v[168:171], v[38:41]
	v_mfma_f32_16x16x32_bf16 v[22:25], v[152:155], v[168:171], v[22:25]
	s_waitcnt lgkmcnt(1)
	v_mfma_f32_16x16x32_bf16 v[50:53], v[144:147], v[172:175], v[50:53]
	v_mfma_f32_16x16x32_bf16 v[34:37], v[148:151], v[172:175], v[34:37]
	v_mfma_f32_16x16x32_bf16 v[18:21], v[152:155], v[172:175], v[18:21]
	s_waitcnt lgkmcnt(0)
	v_mfma_f32_16x16x32_bf16 v[14:17], v[156:159], v[176:179], v[14:17]
	v_mfma_f32_16x16x32_bf16 v[10:13], v[156:159], v[180:183], v[10:13]
	v_mfma_f32_16x16x32_bf16 v[6:9], v[156:159], v[168:171], v[6:9]
	v_mfma_f32_16x16x32_bf16 v[2:5], v[156:159], v[172:175], v[2:5]
	s_cbranch_vccnz .LBB0_329

; DEV unsigned pack2(float a, float b) { f32x2 v = {a, b}; return __builtin_bit_cast(unsigned, __builtin_convertvector(v, bf2_t)); }
; template <class Epi>
; DEV void gemm_tile(const bf16_t* __restrict__ A, int lda, const bf16_t* __restrict__ Bt, int ldb, int K, int m0, int n0,
;                    Epi& epi, char* smem) {
;     ...
; #pragma unroll
;   for (int i = 0; i < 4; i++)
; #pragma unroll
;     for (int j = 0; j < 4; j++) epi(m0 + wm * 64 + j * 16 + l15, n0 + wn * 64 + i * 16 + quad * 4, acc[i][j]);
;   DEV void operator()(int m, int n, f32x4 v) {
;     uint2 r; r.x = pack2(v[0], v[1]); r.y = pack2(v[2], v[3]);
;     *(uint2*)(C + (size_t)m * ldc + n) = r;
;   }
.LBB0_642:
	s_nop 7
	s_nop 7
	v_and_or_b32 v0, v145, 15, s13
	v_add_u32_e32 v2, v0, v146
	v_lshrrev_b32_e32 v0, 2, v145
	v_and_b32_e32 v0, 12, v0
	v_or3_b32 v4, s12, v0, v144
	v_ashrrev_i32_e32 v5, 31, v4
	v_ashrrev_i32_e32 v3, 31, v2
	v_lshl_add_u64 v[4:5], v[4:5], 1, s[0:1]
	s_waitcnt vmcnt(7)
	v_lshlrev_b64 v[8:9], 12, v[2:3]
	v_cvt_pk_bf16_f32 v6, v106, v107
	v_cvt_pk_bf16_f32 v7, v108, v109
	v_lshl_add_u64 v[8:9], v[4:5], 0, v[8:9]
	global_store_dwordx2 v[8:9], v[6:7], off
	v_or_b32_e32 v6, 16, v2
	v_ashrrev_i32_e32 v7, 31, v6
	v_lshlrev_b64 v[6:7], 12, v[6:7]
	v_cvt_pk_bf16_f32 v10, v122, v123
	v_cvt_pk_bf16_f32 v11, v124, v125
	v_lshl_add_u64 v[6:7], v[4:5], 0, v[6:7]
	global_store_dwordx2 v[6:7], v[10:11], off
	v_or_b32_e32 v10, 32, v2
	v_or_b32_e32 v2, 48, v2
	v_ashrrev_i32_e32 v11, 31, v10
	v_ashrrev_i32_e32 v3, 31, v2
	v_lshlrev_b64 v[10:11], 12, v[10:11]
	v_lshlrev_b64 v[2:3], 12, v[2:3]
	v_lshl_add_u64 v[10:11], v[4:5], 0, v[10:11]
	v_lshl_add_u64 v[2:3], v[4:5], 0, v[2:3]
	v_cvt_pk_bf16_f32 v4, v102, v103
	v_cvt_pk_bf16_f32 v5, v104, v105
	global_store_dwordx2 v[8:9], v[4:5], off offset:32
	v_cvt_pk_bf16_f32 v4, v94, v95
	v_cvt_pk_bf16_f32 v5, v96, v97
	global_store_dwordx2 v[6:7], v[4:5], off offset:32
	v_cvt_pk_bf16_f32 v4, v86, v87
	v_cvt_pk_bf16_f32 v5, v88, v89
	global_store_dwordx2 v[10:11], v[4:5], off offset:32
	v_cvt_pk_bf16_f32 v4, v78, v79
	v_cvt_pk_bf16_f32 v5, v80, v81
	global_store_dwordx2 v[2:3], v[4:5], off offset:32
	v_cvt_pk_bf16_f32 v4, v82, v83
	v_cvt_pk_bf16_f32 v5, v84, v85
	global_store_dwordx2 v[8:9], v[4:5], off offset:64
	v_cvt_pk_bf16_f32 v4, v74, v75
	v_cvt_pk_bf16_f32 v5, v76, v77
	global_store_dwordx2 v[6:7], v[4:5], off offset:64
	v_cvt_pk_bf16_f32 v4, v70, v71
	v_cvt_pk_bf16_f32 v5, v72, v73
	global_store_dwordx2 v[10:11], v[4:5], off offset:64
	v_cvt_pk_bf16_f32 v4, v66, v67
	v_cvt_pk_bf16_f32 v5, v68, v69
	global_store_dwordx2 v[2:3], v[4:5], off offset:64
	v_cvt_pk_bf16_f32 v4, v98, v99
	v_cvt_pk_bf16_f32 v5, v100, v101
	global_store_dwordx2 v[8:9], v[4:5], off offset:96
	v_cvt_pk_bf16_f32 v4, v90, v91
	v_cvt_pk_bf16_f32 v5, v92, v93
	v_cvt_pk_bf16_f32 v12, v114, v115
	v_cvt_pk_bf16_f32 v13, v116, v117
	global_store_dwordx2 v[6:7], v[4:5], off offset:96
	v_cvt_pk_bf16_f32 v4, v126, v127
	v_cvt_pk_bf16_f32 v5, v128, v129
	global_store_dwordx2 v[10:11], v[12:13], off
	v_cvt_pk_bf16_f32 v12, v110, v111
	v_cvt_pk_bf16_f32 v13, v112, v113
	global_store_dwordx2 v[10:11], v[4:5], off offset:96
	v_cvt_pk_bf16_f32 v4, v118, v119
	v_cvt_pk_bf16_f32 v5, v120, v121
	global_store_dwordx2 v[2:3], v[12:13], off
	global_store_dwordx2 v[2:3], v[4:5], off offset:96

; DEV f32x4 mfma16(bf16x8 a, bf16x8 b, f32x4 c) { return __builtin_amdgcn_mfma_f32_16x16x32_bf16(a, b, c, 0, 0, 0); }
; template <int TI, int TJ, int KS>
; DEV void mfma_lds(const bf16_t* Arows, int lda, const bf16_t* Brows, int ldb, int i0, int j0, f32x4 (&acc)[TI][TJ]) {
;     ...
;   for (int ks = 0; ks < KS; ks++) {
;     bf16x8 af[TI], bfr[TJ];
; #pragma unroll
;     for (int i = 0; i < TI; i++) af[i] = *(const bf16x8*)(Arows + (i0 + i * 16 + l15) * lda + ks * 32 + quad * 8);
; #pragma unroll
;     for (int j = 0; j < TJ; j++) bfr[j] = *(const bf16x8*)(Brows + (j0 + j * 16 + l15) * ldb + ks * 32 + quad * 8);
; #pragma unroll
;     for (int i = 0; i < TI; i++)
; #pragma unroll
;       for (int j = 0; j < TJ; j++) acc[i][j] = mfma16(af[i], bfr[j], acc[i][j]);
;   }
.LBB0_646:
	v_mov_b32_e32 v130, v195
	v_and_b32_e32 v135, 15, v130
	v_or_b32_e32 v131, v135, v144
	v_and_b32_e32 v148, 48, v130
	v_mul_u32_u24_e32 v130, 0x50, v131
	v_lshl_add_u32 v147, v130, 1, v148
	v_or_b32_e32 v135, v135, v146
	v_mad_u32_u24 v238, v135, s36, v148
	v_lshl_add_u64 v[136:137], v[136:137], 0, s[34:35]
	v_lshl_add_u64 v[138:139], v[138:139], 0, s[34:35]
	s_andn2_b64 vcc, exec, s[8:9]
	ds_read_b128 v[148:151], v147 offset:20480
	ds_read_b128 v[164:167], v238
	ds_read_b128 v[168:171], v238 offset:2560
	ds_read_b128 v[172:175], v238 offset:5120
	ds_read_b128 v[176:179], v238 offset:7680
	ds_read_b128 v[152:155], v147 offset:23040
	ds_read_b128 v[156:159], v147 offset:25600
	ds_read_b128 v[160:163], v147 offset:28160
	ds_read_b128 v[180:183], v238 offset:64
	ds_read_b128 v[184:187], v238 offset:2624
	s_waitcnt lgkmcnt(8)
	v_mfma_f32_16x16x32_bf16 v[106:109], v[148:151], v[164:167], v[106:109]
	s_waitcnt lgkmcnt(7)
	v_mfma_f32_16x16x32_bf16 v[122:125], v[148:151], v[168:171], v[122:125]
	s_waitcnt lgkmcnt(6)
	v_mfma_f32_16x16x32_bf16 v[114:117], v[148:151], v[172:175], v[114:117]
	s_waitcnt lgkmcnt(5)
	v_mfma_f32_16x16x32_bf16 v[110:113], v[148:151], v[176:179], v[110:113]
	ds_read_b128 v[148:151], v147 offset:20544
	s_waitcnt lgkmcnt(5)
	v_mfma_f32_16x16x32_bf16 v[102:105], v[152:155], v[164:167], v[102:105]
	v_mfma_f32_16x16x32_bf16 v[94:97], v[152:155], v[168:171], v[94:97]
	v_mfma_f32_16x16x32_bf16 v[86:89], v[152:155], v[172:175], v[86:89]
	v_mfma_f32_16x16x32_bf16 v[78:81], v[152:155], v[176:179], v[78:81]
	ds_read_b128 v[152:155], v147 offset:23104
	s_waitcnt lgkmcnt(5)
	v_mfma_f32_16x16x32_bf16 v[82:85], v[156:159], v[164:167], v[82:85]
	v_mfma_f32_16x16x32_bf16 v[74:77], v[156:159], v[168:171], v[74:77]
	v_mfma_f32_16x16x32_bf16 v[70:73], v[156:159], v[172:175], v[70:73]
	v_mfma_f32_16x16x32_bf16 v[66:69], v[156:159], v[176:179], v[66:69]
	ds_read_b128 v[156:159], v147 offset:25664
	s_waitcnt lgkmcnt(5)
	v_mfma_f32_16x16x32_bf16 v[126:129], v[160:163], v[172:175], v[126:129]
	v_mfma_f32_16x16x32_bf16 v[118:121], v[160:163], v[176:179], v[118:121]
	ds_read_b128 v[172:175], v238 offset:5184
	ds_read_b128 v[176:179], v238 offset:7744
	v_mfma_f32_16x16x32_bf16 v[98:101], v[160:163], v[164:167], v[98:101]
	v_mfma_f32_16x16x32_bf16 v[90:93], v[160:163], v[168:171], v[90:93]
	ds_read_b128 v[160:163], v147 offset:28224
	s_waitcnt lgkmcnt(5)
	v_mfma_f32_16x16x32_bf16 v[106:109], v[148:151], v[180:183], v[106:109]
	s_waitcnt lgkmcnt(4)
	v_mfma_f32_16x16x32_bf16 v[102:105], v[152:155], v[180:183], v[102:105]
	s_waitcnt lgkmcnt(3)
	v_mfma_f32_16x16x32_bf16 v[82:85], v[156:159], v[180:183], v[82:85]
	v_mfma_f32_16x16x32_bf16 v[122:125], v[148:151], v[184:187], v[122:125]
	v_mfma_f32_16x16x32_bf16 v[94:97], v[152:155], v[184:187], v[94:97]
	v_mfma_f32_16x16x32_bf16 v[74:77], v[156:159], v[184:187], v[74:77]
	s_waitcnt lgkmcnt(2)
	v_mfma_f32_16x16x32_bf16 v[114:117], v[148:151], v[172:175], v[114:117]
	v_mfma_f32_16x16x32_bf16 v[86:89], v[152:155], v[172:175], v[86:89]
	v_mfma_f32_16x16x32_bf16 v[70:73], v[156:159], v[172:175], v[70:73]
	s_waitcnt lgkmcnt(1)
	v_mfma_f32_16x16x32_bf16 v[110:113], v[148:151], v[176:179], v[110:113]
	v_mfma_f32_16x16x32_bf16 v[78:81], v[152:155], v[176:179], v[78:81]
	v_mfma_f32_16x16x32_bf16 v[66:69], v[156:159], v[176:179], v[66:69]
	s_waitcnt lgkmcnt(0)
	v_mfma_f32_16x16x32_bf16 v[98:101], v[160:163], v[180:183], v[98:101]
	v_mfma_f32_16x16x32_bf16 v[90:93], v[160:163], v[184:187], v[90:93]
	v_mfma_f32_16x16x32_bf16 v[126:129], v[160:163], v[172:175], v[126:129]
	v_mfma_f32_16x16x32_bf16 v[118:121], v[160:163], v[176:179], v[118:121]
	s_cbranch_vccz .LBB0_642

; DEV f32x4 mfma16(bf16x8 a, bf16x8 b, f32x4 c) { return __builtin_amdgcn_mfma_f32_16x16x32_bf16(a, b, c, 0, 0, 0); }
; #define G_LOAD(RA, RB, KT) { _Pragma("unroll") for (int i = 0; i < 4; i++) { \
;       RA[i] = *(const u32x4*)(Ap + (size_t)(i * 32) * lda + (KT) * 64); RB[i] = *(const u32x4*)(Bp + (size_t)(i * 32) * ldb + (KT) * 64); } }
; #define G_STORE(RA, RB) { _Pragma("unroll") for (int i = 0; i < 4; i++) { \
;       *(u32x4*)(As + (lrow + i * 32) * GLD + lcc * 8) = RA[i]; *(u32x4*)(Bs + (lrow + i * 32) * GLD + lcc * 8) = RB[i]; } }
; template <int TI, int TJ, int KS>
; DEV void mfma_lds(const bf16_t* Arows, int lda, const bf16_t* Brows, int ldb, int i0, int j0, f32x4 (&acc)[TI][TJ]) {
;     ...
;   for (int ks = 0; ks < KS; ks++) {
;     bf16x8 af[TI], bfr[TJ];
; #pragma unroll
;     for (int i = 0; i < TI; i++) af[i] = *(const bf16x8*)(Arows + (i0 + i * 16 + l15) * lda + ks * 32 + quad * 8);
; #pragma unroll
;     for (int j = 0; j < TJ; j++) bfr[j] = *(const bf16x8*)(Brows + (j0 + j * 16 + l15) * ldb + ks * 32 + quad * 8);
; #pragma unroll
;     for (int i = 0; i < TI; i++)
; #pragma unroll
;       for (int j = 0; j < TJ; j++) acc[i][j] = mfma16(af[i], bfr[j], acc[i][j]);
;   }
; template <class Epi>
; DEV void gemm_tile(const bf16_t* __restrict__ A, int lda, const bf16_t* __restrict__ Bt, int ldb, int K, int m0, int n0,
;                    Epi& epi, char* smem) {
;     ...
;   for (int kt = 0; kt < nk; kt += 2) {
;     __syncthreads();
;     G_STORE(ra0, rb0);
;     __syncthreads();
;     if (kt + 2 < nk) G_LOAD(ra0, rb0, kt + 2);
;     mfma_lds<4, 4, 2>(Bs, GLD, As, GLD, wn * 64, wm * 64, acc);
;     __syncthreads();
;     G_STORE(ra1, rb1);
;     __syncthreads();
;     if (kt + 3 < nk) G_LOAD(ra1, rb1, kt + 3);
;     mfma_lds<4, 4, 2>(Bs, GLD, As, GLD, wn * 64, wm * 64, acc);
;   }
.LBB0_649:
	v_mov_b32_e32 v130, v195
	s_cmp_gt_u32 s14, 12
	v_and_b32_e32 v135, 15, v130
	v_or_b32_e32 v131, v135, v144
	v_and_b32_e32 v148, 48, v130
	v_mul_u32_u24_e32 v130, 0x50, v131
	v_lshl_add_u32 v147, v130, 1, v148
	v_or_b32_e32 v135, v135, v146
	v_mad_u32_u24 v238, v135, s36, v148
	ds_read_b128 v[148:151], v147 offset:20480
	ds_read_b128 v[164:167], v238
	ds_read_b128 v[168:171], v238 offset:2560
	ds_read_b128 v[172:175], v238 offset:5120
	ds_read_b128 v[176:179], v238 offset:7680
	ds_read_b128 v[152:155], v147 offset:23040
	ds_read_b128 v[156:159], v147 offset:25600
	ds_read_b128 v[160:163], v147 offset:28160
	ds_read_b128 v[180:183], v238 offset:64
	ds_read_b128 v[184:187], v238 offset:2624
	s_waitcnt lgkmcnt(8)
	v_mfma_f32_16x16x32_bf16 v[106:109], v[148:151], v[164:167], v[106:109]
	s_waitcnt lgkmcnt(7)
	v_mfma_f32_16x16x32_bf16 v[122:125], v[148:151], v[168:171], v[122:125]
	s_waitcnt lgkmcnt(6)
	v_mfma_f32_16x16x32_bf16 v[114:117], v[148:151], v[172:175], v[114:117]
	s_waitcnt lgkmcnt(5)
	v_mfma_f32_16x16x32_bf16 v[110:113], v[148:151], v[176:179], v[110:113]
	ds_read_b128 v[148:151], v147 offset:20544
	s_waitcnt lgkmcnt(5)
	v_mfma_f32_16x16x32_bf16 v[102:105], v[152:155], v[164:167], v[102:105]
	v_mfma_f32_16x16x32_bf16 v[94:97], v[152:155], v[168:171], v[94:97]
	v_mfma_f32_16x16x32_bf16 v[86:89], v[152:155], v[172:175], v[86:89]
	v_mfma_f32_16x16x32_bf16 v[78:81], v[152:155], v[176:179], v[78:81]
	ds_read_b128 v[152:155], v147 offset:23104
	s_waitcnt lgkmcnt(5)
	v_mfma_f32_16x16x32_bf16 v[82:85], v[156:159], v[164:167], v[82:85]
	v_mfma_f32_16x16x32_bf16 v[74:77], v[156:159], v[168:171], v[74:77]
	v_mfma_f32_16x16x32_bf16 v[70:73], v[156:159], v[172:175], v[70:73]
	v_mfma_f32_16x16x32_bf16 v[66:69], v[156:159], v[176:179], v[66:69]
	ds_read_b128 v[156:159], v147 offset:25664
	s_waitcnt lgkmcnt(5)
	v_mfma_f32_16x16x32_bf16 v[126:129], v[160:163], v[172:175], v[126:129]
	v_mfma_f32_16x16x32_bf16 v[118:121], v[160:163], v[176:179], v[118:121]
	ds_read_b128 v[172:175], v238 offset:5184
	ds_read_b128 v[176:179], v238 offset:7744
	v_mfma_f32_16x16x32_bf16 v[98:101], v[160:163], v[164:167], v[98:101]
	v_mfma_f32_16x16x32_bf16 v[90:93], v[160:163], v[168:171], v[90:93]
	ds_read_b128 v[160:163], v147 offset:28224
	s_waitcnt lgkmcnt(5)
	v_mfma_f32_16x16x32_bf16 v[106:109], v[148:151], v[180:183], v[106:109]
	s_waitcnt lgkmcnt(4)
	v_mfma_f32_16x16x32_bf16 v[102:105], v[152:155], v[180:183], v[102:105]
	s_waitcnt lgkmcnt(3)
	v_mfma_f32_16x16x32_bf16 v[82:85], v[156:159], v[180:183], v[82:85]
	v_mfma_f32_16x16x32_bf16 v[122:125], v[148:151], v[184:187], v[122:125]
	v_mfma_f32_16x16x32_bf16 v[94:97], v[152:155], v[184:187], v[94:97]
	v_mfma_f32_16x16x32_bf16 v[74:77], v[156:159], v[184:187], v[74:77]
	s_waitcnt lgkmcnt(2)
	v_mfma_f32_16x16x32_bf16 v[114:117], v[148:151], v[172:175], v[114:117]
	v_mfma_f32_16x16x32_bf16 v[86:89], v[152:155], v[172:175], v[86:89]
	v_mfma_f32_16x16x32_bf16 v[70:73], v[156:159], v[172:175], v[70:73]
	s_waitcnt lgkmcnt(1)
	v_mfma_f32_16x16x32_bf16 v[110:113], v[148:151], v[176:179], v[110:113]
	v_mfma_f32_16x16x32_bf16 v[78:81], v[152:155], v[176:179], v[78:81]
	v_mfma_f32_16x16x32_bf16 v[66:69], v[156:159], v[176:179], v[66:69]
	s_waitcnt lgkmcnt(0)
	v_mfma_f32_16x16x32_bf16 v[98:101], v[160:163], v[180:183], v[98:101]
	s_barrier
	v_mfma_f32_16x16x32_bf16 v[90:93], v[160:163], v[184:187], v[90:93]
	s_waitcnt vmcnt(8)
	ds_write_b128 v134, v[6:9]
	ds_write_b128 v134, v[14:17] offset:20480
	ds_write_b128 v134, v[22:25] offset:5120
	ds_write_b128 v134, v[30:33] offset:25600
	ds_write_b128 v134, v[38:41] offset:10240
	ds_write_b128 v134, v[46:49] offset:30720
	ds_write_b128 v134, v[54:57] offset:15360
	ds_write_b128 v134, v[62:65] offset:35840
	v_mfma_f32_16x16x32_bf16 v[126:129], v[160:163], v[172:175], v[126:129]
	s_waitcnt lgkmcnt(0)
	s_barrier
	v_mfma_f32_16x16x32_bf16 v[118:121], v[160:163], v[176:179], v[118:121]
	s_cbranch_scc1 .LBB0_646
	v_add_co_u32_e32 v6, vcc, 0x4200000, v142
	s_nop 1
	v_addc_co_u32_e32 v7, vcc, 0, v143, vcc
	v_add_co_u32_e32 v14, vcc, 0xb5c0000, v140
	global_load_dwordx4 v[6:9], v[6:7], off offset:384
	s_nop 0
	v_addc_co_u32_e32 v15, vcc, 0, v141, vcc
	v_add_co_u32_e32 v22, vcc, 0x4211000, v142
	global_load_dwordx4 v[14:17], v[14:15], off offset:384
	s_nop 0
	v_addc_co_u32_e32 v23, vcc, 0, v143, vcc
	v_add_co_u32_e32 v30, vcc, 0xb5d1000, v140
	global_load_dwordx4 v[22:25], v[22:23], off offset:384
	s_nop 0
	v_addc_co_u32_e32 v31, vcc, 0, v141, vcc
	v_add_co_u32_e32 v38, vcc, 0x4222000, v142
	global_load_dwordx4 v[30:33], v[30:31], off offset:384
	s_nop 0
	v_addc_co_u32_e32 v39, vcc, 0, v143, vcc
	v_add_co_u32_e32 v46, vcc, 0xb5e2000, v140
	global_load_dwordx4 v[38:41], v[38:39], off offset:384
	s_nop 0
	v_addc_co_u32_e32 v47, vcc, 0, v141, vcc
	v_add_co_u32_e32 v54, vcc, 0x4233000, v142
	global_load_dwordx4 v[46:49], v[46:47], off offset:384
	s_nop 0
	v_addc_co_u32_e32 v55, vcc, 0, v143, vcc
	v_add_co_u32_e32 v62, vcc, 0xb5f3000, v140
	global_load_dwordx4 v[54:57], v[54:55], off offset:384
	s_nop 0
	v_addc_co_u32_e32 v63, vcc, 0, v141, vcc
	global_load_dwordx4 v[62:65], v[62:63], off offset:384
	s_branch .LBB0_646

; DEV f32x4 mfma16(bf16x8 a, bf16x8 b, f32x4 c) { return __builtin_amdgcn_mfma_f32_16x16x32_bf16(a, b, c, 0, 0, 0); }
; template <int TI, int TJ, int KS>
; DEV void mfma_lds(const bf16_t* Arows, int lda, const bf16_t* Brows, int ldb, int i0, int j0, f32x4 (&acc)[TI][TJ]) {
;     ...
;   for (int ks = 0; ks < KS; ks++) {
;     bf16x8 af[TI], bfr[TJ];
; #pragma unroll
;     for (int i = 0; i < TI; i++) af[i] = *(const bf16x8*)(Arows + (i0 + i * 16 + l15) * lda + ks * 32 + quad * 8);
; #pragma unroll
;     for (int j = 0; j < TJ; j++) bfr[j] = *(const bf16x8*)(Brows + (j0 + j * 16 + l15) * ldb + ks * 32 + quad * 8);
; #pragma unroll
;     for (int i = 0; i < TI; i++)
; #pragma unroll
;       for (int j = 0; j < TJ; j++) acc[i][j] = mfma16(af[i], bfr[j], acc[i][j]);
;   }
.LBB0_670:
	v_mov_b32_e32 v131, v195
	v_and_b32_e32 v143, 15, v131
	v_or_b32_e32 v144, v143, v140
	v_and_b32_e32 v148, 48, v131
	v_mul_u32_u24_e32 v131, 0x50, v144
	v_lshl_add_u32 v131, v131, 1, v148
	v_or_b32_e32 v143, v143, v142
	v_mad_u32_u24 v238, v143, s36, v148
	v_lshl_add_u64 v[132:133], v[132:133], 0, s[34:35]
	v_lshl_add_u64 v[134:135], v[134:135], 0, s[34:35]
	s_and_b64 vcc, exec, s[8:9]
	ds_read_b128 v[144:147], v131 offset:20480
	ds_read_b128 v[160:163], v238
	ds_read_b128 v[164:167], v238 offset:2560
	ds_read_b128 v[168:171], v238 offset:5120
	ds_read_b128 v[172:175], v238 offset:7680
	ds_read_b128 v[148:151], v131 offset:23040
	ds_read_b128 v[152:155], v131 offset:25600
	ds_read_b128 v[156:159], v131 offset:28160
	ds_read_b128 v[176:179], v238 offset:64
	ds_read_b128 v[180:183], v238 offset:2624
	s_waitcnt lgkmcnt(8)
	v_mfma_f32_16x16x32_bf16 v[126:129], v[144:147], v[160:163], v[126:129]
	s_waitcnt lgkmcnt(7)
	v_mfma_f32_16x16x32_bf16 v[122:125], v[144:147], v[164:167], v[122:125]
	s_waitcnt lgkmcnt(6)
	v_mfma_f32_16x16x32_bf16 v[118:121], v[144:147], v[168:171], v[118:121]
	s_waitcnt lgkmcnt(5)
	v_mfma_f32_16x16x32_bf16 v[114:117], v[144:147], v[172:175], v[114:117]
	ds_read_b128 v[144:147], v131 offset:20544
	s_waitcnt lgkmcnt(5)
	v_mfma_f32_16x16x32_bf16 v[110:113], v[148:151], v[160:163], v[110:113]
	v_mfma_f32_16x16x32_bf16 v[58:61], v[148:151], v[164:167], v[58:61]
	v_mfma_f32_16x16x32_bf16 v[38:41], v[148:151], v[168:171], v[38:41]
	v_mfma_f32_16x16x32_bf16 v[34:37], v[148:151], v[172:175], v[34:37]
	ds_read_b128 v[148:151], v131 offset:23104
	s_waitcnt lgkmcnt(5)
	v_mfma_f32_16x16x32_bf16 v[30:33], v[152:155], v[160:163], v[30:33]
	v_mfma_f32_16x16x32_bf16 v[26:29], v[152:155], v[164:167], v[26:29]
	v_mfma_f32_16x16x32_bf16 v[22:25], v[152:155], v[168:171], v[22:25]
	v_mfma_f32_16x16x32_bf16 v[18:21], v[152:155], v[172:175], v[18:21]
	ds_read_b128 v[152:155], v131 offset:25664
	s_waitcnt lgkmcnt(5)
	v_mfma_f32_16x16x32_bf16 v[6:9], v[156:159], v[168:171], v[6:9]
	v_mfma_f32_16x16x32_bf16 v[2:5], v[156:159], v[172:175], v[2:5]
	ds_read_b128 v[168:171], v238 offset:5184
	ds_read_b128 v[172:175], v238 offset:7744
	v_mfma_f32_16x16x32_bf16 v[14:17], v[156:159], v[160:163], v[14:17]
	v_mfma_f32_16x16x32_bf16 v[10:13], v[156:159], v[164:167], v[10:13]
	ds_read_b128 v[156:159], v131 offset:28224
	s_waitcnt lgkmcnt(5)
	v_mfma_f32_16x16x32_bf16 v[126:129], v[144:147], v[176:179], v[126:129]
	s_waitcnt lgkmcnt(4)
	v_mfma_f32_16x16x32_bf16 v[110:113], v[148:151], v[176:179], v[110:113]
	s_waitcnt lgkmcnt(3)
	v_mfma_f32_16x16x32_bf16 v[30:33], v[152:155], v[176:179], v[30:33]
	v_mfma_f32_16x16x32_bf16 v[122:125], v[144:147], v[180:183], v[122:125]
	v_mfma_f32_16x16x32_bf16 v[58:61], v[148:151], v[180:183], v[58:61]
	v_mfma_f32_16x16x32_bf16 v[26:29], v[152:155], v[180:183], v[26:29]
	s_waitcnt lgkmcnt(2)
	v_mfma_f32_16x16x32_bf16 v[118:121], v[144:147], v[168:171], v[118:121]
	v_mfma_f32_16x16x32_bf16 v[38:41], v[148:151], v[168:171], v[38:41]
	v_mfma_f32_16x16x32_bf16 v[22:25], v[152:155], v[168:171], v[22:25]
	s_waitcnt lgkmcnt(1)
	v_mfma_f32_16x16x32_bf16 v[114:117], v[144:147], v[172:175], v[114:117]
	v_mfma_f32_16x16x32_bf16 v[34:37], v[148:151], v[172:175], v[34:37]
	v_mfma_f32_16x16x32_bf16 v[18:21], v[152:155], v[172:175], v[18:21]
	s_waitcnt lgkmcnt(0)
	v_mfma_f32_16x16x32_bf16 v[14:17], v[156:159], v[176:179], v[14:17]
	v_mfma_f32_16x16x32_bf16 v[10:13], v[156:159], v[180:183], v[10:13]
	v_mfma_f32_16x16x32_bf16 v[6:9], v[156:159], v[168:171], v[6:9]
	v_mfma_f32_16x16x32_bf16 v[2:5], v[156:159], v[172:175], v[2:5]
	s_cbranch_vccnz .LBB0_675

; DEV f32x4 mfma16(bf16x8 a, bf16x8 b, f32x4 c) { return __builtin_amdgcn_mfma_f32_16x16x32_bf16(a, b, c, 0, 0, 0); }
; #define G_LOAD(RA, RB, KT) { _Pragma("unroll") for (int i = 0; i < 4; i++) { \
;       RA[i] = *(const u32x4*)(Ap + (size_t)(i * 32) * lda + (KT) * 64); RB[i] = *(const u32x4*)(Bp + (size_t)(i * 32) * ldb + (KT) * 64); } }
; #define G_STORE(RA, RB) { _Pragma("unroll") for (int i = 0; i < 4; i++) { \
;       *(u32x4*)(As + (lrow + i * 32) * GLD + lcc * 8) = RA[i]; *(u32x4*)(Bs + (lrow + i * 32) * GLD + lcc * 8) = RB[i]; } }
; template <int TI, int TJ, int KS>
; DEV void mfma_lds(const bf16_t* Arows, int lda, const bf16_t* Brows, int ldb, int i0, int j0, f32x4 (&acc)[TI][TJ]) {
;     ...
;   for (int ks = 0; ks < KS; ks++) {
;     bf16x8 af[TI], bfr[TJ];
; #pragma unroll
;     for (int i = 0; i < TI; i++) af[i] = *(const bf16x8*)(Arows + (i0 + i * 16 + l15) * lda + ks * 32 + quad * 8);
; #pragma unroll
;     for (int j = 0; j < TJ; j++) bfr[j] = *(const bf16x8*)(Brows + (j0 + j * 16 + l15) * ldb + ks * 32 + quad * 8);
; #pragma unroll
;     for (int i = 0; i < TI; i++)
; #pragma unroll
;       for (int j = 0; j < TJ; j++) acc[i][j] = mfma16(af[i], bfr[j], acc[i][j]);
;   }
; template <class Epi>
; DEV void gemm_tile(const bf16_t* __restrict__ A, int lda, const bf16_t* __restrict__ Bt, int ldb, int K, int m0, int n0,
;                    Epi& epi, char* smem) {
;     ...
;   for (int kt = 0; kt < nk; kt += 2) {
;     __syncthreads();
;     G_STORE(ra0, rb0);
;     __syncthreads();
;     if (kt + 2 < nk) G_LOAD(ra0, rb0, kt + 2);
;     mfma_lds<4, 4, 2>(Bs, GLD, As, GLD, wn * 64, wm * 64, acc);
;     __syncthreads();
;     G_STORE(ra1, rb1);
;     __syncthreads();
;     if (kt + 3 < nk) G_LOAD(ra1, rb1, kt + 3);
;     mfma_lds<4, 4, 2>(Bs, GLD, As, GLD, wn * 64, wm * 64, acc);
;   }
.LBB0_673:
	v_mov_b32_e32 v131, v195
	s_cmp_gt_u32 s15, 12
	v_and_b32_e32 v143, 15, v131
	v_or_b32_e32 v144, v143, v140
	v_and_b32_e32 v148, 48, v131
	v_mul_u32_u24_e32 v131, 0x50, v144
	v_lshl_add_u32 v131, v131, 1, v148
	v_or_b32_e32 v143, v143, v142
	v_mad_u32_u24 v238, v143, s36, v148
	ds_read_b128 v[144:147], v131 offset:20480
	ds_read_b128 v[160:163], v238
	ds_read_b128 v[164:167], v238 offset:2560
	ds_read_b128 v[168:171], v238 offset:5120
	ds_read_b128 v[172:175], v238 offset:7680
	ds_read_b128 v[148:151], v131 offset:23040
	ds_read_b128 v[152:155], v131 offset:25600
	ds_read_b128 v[156:159], v131 offset:28160
	ds_read_b128 v[176:179], v238 offset:64
	ds_read_b128 v[180:183], v238 offset:2624
	s_waitcnt lgkmcnt(8)
	v_mfma_f32_16x16x32_bf16 v[126:129], v[144:147], v[160:163], v[126:129]
	s_waitcnt lgkmcnt(7)
	v_mfma_f32_16x16x32_bf16 v[122:125], v[144:147], v[164:167], v[122:125]
	s_waitcnt lgkmcnt(6)
	v_mfma_f32_16x16x32_bf16 v[118:121], v[144:147], v[168:171], v[118:121]
	s_waitcnt lgkmcnt(5)
	v_mfma_f32_16x16x32_bf16 v[114:117], v[144:147], v[172:175], v[114:117]
	ds_read_b128 v[144:147], v131 offset:20544
	s_waitcnt lgkmcnt(5)
	v_mfma_f32_16x16x32_bf16 v[110:113], v[148:151], v[160:163], v[110:113]
	v_mfma_f32_16x16x32_bf16 v[58:61], v[148:151], v[164:167], v[58:61]
	v_mfma_f32_16x16x32_bf16 v[38:41], v[148:151], v[168:171], v[38:41]
	v_mfma_f32_16x16x32_bf16 v[34:37], v[148:151], v[172:175], v[34:37]
	ds_read_b128 v[148:151], v131 offset:23104
	s_waitcnt lgkmcnt(5)
	v_mfma_f32_16x16x32_bf16 v[30:33], v[152:155], v[160:163], v[30:33]
	v_mfma_f32_16x16x32_bf16 v[26:29], v[152:155], v[164:167], v[26:29]
	v_mfma_f32_16x16x32_bf16 v[22:25], v[152:155], v[168:171], v[22:25]
	v_mfma_f32_16x16x32_bf16 v[18:21], v[152:155], v[172:175], v[18:21]
	ds_read_b128 v[152:155], v131 offset:25664
	s_waitcnt lgkmcnt(5)
	v_mfma_f32_16x16x32_bf16 v[6:9], v[156:159], v[168:171], v[6:9]
	v_mfma_f32_16x16x32_bf16 v[2:5], v[156:159], v[172:175], v[2:5]
	ds_read_b128 v[168:171], v238 offset:5184
	ds_read_b128 v[172:175], v238 offset:7744
	v_mfma_f32_16x16x32_bf16 v[14:17], v[156:159], v[160:163], v[14:17]
	v_mfma_f32_16x16x32_bf16 v[10:13], v[156:159], v[164:167], v[10:13]
	ds_read_b128 v[156:159], v131 offset:28224
	s_waitcnt lgkmcnt(5)
	v_mfma_f32_16x16x32_bf16 v[126:129], v[144:147], v[176:179], v[126:129]
	s_waitcnt lgkmcnt(4)
	v_mfma_f32_16x16x32_bf16 v[110:113], v[148:151], v[176:179], v[110:113]
	s_waitcnt lgkmcnt(3)
	v_mfma_f32_16x16x32_bf16 v[30:33], v[152:155], v[176:179], v[30:33]
	v_mfma_f32_16x16x32_bf16 v[122:125], v[144:147], v[180:183], v[122:125]
	v_mfma_f32_16x16x32_bf16 v[58:61], v[148:151], v[180:183], v[58:61]
	v_mfma_f32_16x16x32_bf16 v[26:29], v[152:155], v[180:183], v[26:29]
	s_waitcnt lgkmcnt(2)
	v_mfma_f32_16x16x32_bf16 v[118:121], v[144:147], v[168:171], v[118:121]
	v_mfma_f32_16x16x32_bf16 v[38:41], v[148:151], v[168:171], v[38:41]
	v_mfma_f32_16x16x32_bf16 v[22:25], v[152:155], v[168:171], v[22:25]
	s_waitcnt lgkmcnt(1)
	v_mfma_f32_16x16x32_bf16 v[114:117], v[144:147], v[172:175], v[114:117]
	v_mfma_f32_16x16x32_bf16 v[34:37], v[148:151], v[172:175], v[34:37]
	v_mfma_f32_16x16x32_bf16 v[18:21], v[152:155], v[172:175], v[18:21]
	s_waitcnt lgkmcnt(0)
	v_mfma_f32_16x16x32_bf16 v[14:17], v[156:159], v[176:179], v[14:17]
	s_barrier
	v_mfma_f32_16x16x32_bf16 v[10:13], v[156:159], v[180:183], v[10:13]
	s_waitcnt vmcnt(8)
	ds_write_b128 v130, v[46:49]
	ds_write_b128 v130, v[54:57] offset:20480
	ds_write_b128 v130, v[66:69] offset:5120
	ds_write_b128 v130, v[74:77] offset:25600
	ds_write_b128 v130, v[82:85] offset:10240
	ds_write_b128 v130, v[90:93] offset:30720
	ds_write_b128 v130, v[98:101] offset:15360
	ds_write_b128 v130, v[106:109] offset:35840
	v_mfma_f32_16x16x32_bf16 v[6:9], v[156:159], v[168:171], v[6:9]
	s_waitcnt lgkmcnt(0)
	s_barrier
	v_mfma_f32_16x16x32_bf16 v[2:5], v[156:159], v[172:175], v[2:5]
	s_cbranch_scc1 .LBB0_670
	v_add_co_u32_e32 v46, vcc, 0x19700000, v138
	s_nop 1
	v_addc_co_u32_e32 v47, vcc, 0, v139, vcc
	v_add_co_u32_e32 v54, vcc, 0xa6e0000, v136
	global_load_dwordx4 v[46:49], v[46:47], off offset:384
	s_nop 0
	v_addc_co_u32_e32 v55, vcc, 0, v137, vcc
	v_add_co_u32_e32 v66, vcc, 0x19711000, v138
	global_load_dwordx4 v[54:57], v[54:55], off offset:384
	s_nop 0
	v_addc_co_u32_e32 v67, vcc, 0, v139, vcc
	v_add_co_u32_e32 v74, vcc, 0xa6f1000, v136
	global_load_dwordx4 v[66:69], v[66:67], off offset:384
	s_nop 0
	v_addc_co_u32_e32 v75, vcc, 0, v137, vcc
	v_add_co_u32_e32 v82, vcc, 0x19722000, v138
	global_load_dwordx4 v[74:77], v[74:75], off offset:384
	s_nop 0
	v_addc_co_u32_e32 v83, vcc, 0, v139, vcc
	v_add_co_u32_e32 v90, vcc, 0xa702000, v136
	global_load_dwordx4 v[82:85], v[82:83], off offset:384
	s_nop 0
	v_addc_co_u32_e32 v91, vcc, 0, v137, vcc
	v_add_co_u32_e32 v98, vcc, 0x19733000, v138
	global_load_dwordx4 v[90:93], v[90:91], off offset:384
	s_nop 0
	v_addc_co_u32_e32 v99, vcc, 0, v139, vcc
	v_add_co_u32_e32 v106, vcc, 0xa713000, v136
	global_load_dwordx4 v[98:101], v[98:99], off offset:384
	s_nop 0
	v_addc_co_u32_e32 v107, vcc, 0, v137, vcc
	global_load_dwordx4 v[106:109], v[106:107], off offset:384
	s_branch .LBB0_670

;   DEV void operator()(int m, int n, f32x4 v) {
;     const float* src; int mr;
;     if (m < MM) { src = xin_main + (size_t)m * 1024 + n; mr = m >> 13; } else { src = xin_ctx + (size_t)(m - MM) * 1024 + n; mr = 2; }
;     float4 xo = *(const float4*)src;
.LBB0_675:
	s_nop 7
	s_nop 7
	v_and_or_b32 v0, v141, 15, s14
	v_add_u32_e32 v44, v0, v142
	v_cmp_lt_i32_e64 s[38:39], s23, v44
	s_waitcnt vmcnt(7)
	v_add_u32_e32 v48, 0xffffc000, v44
	s_and_saveexec_b64 s[8:9], s[38:39]
	s_xor_b64 s[8:9], exec, s[8:9]
	s_cbranch_execz .LBB0_677
	v_mov_b32_e32 v49, v1
	v_readlane_b32 s14, v253, 17
	v_lshlrev_b64 v[42:43], 12, v[48:49]
	v_readlane_b32 s15, v253, 18
	v_mov_b32_e32 v45, v1
	v_lshlrev_b64 v[46:47], 12, v[44:45]
	v_lshl_add_u64 v[50:51], s[14:15], 0, v[42:43]

; DEV f32x4 mfma16(bf16x8 a, bf16x8 b, f32x4 c) { return __builtin_amdgcn_mfma_f32_16x16x32_bf16(a, b, c, 0, 0, 0); }
; template <int TI, int TJ, int KS>
; DEV void mfma_lds(const bf16_t* Arows, int lda, const bf16_t* Brows, int ldb, int i0, int j0, f32x4 (&acc)[TI][TJ]) {
;     ...
;   for (int ks = 0; ks < KS; ks++) {
;     bf16x8 af[TI], bfr[TJ];
; #pragma unroll
;     for (int i = 0; i < TI; i++) af[i] = *(const bf16x8*)(Arows + (i0 + i * 16 + l15) * lda + ks * 32 + quad * 8);
; #pragma unroll
;     for (int j = 0; j < TJ; j++) bfr[j] = *(const bf16x8*)(Brows + (j0 + j * 16 + l15) * ldb + ks * 32 + quad * 8);
; #pragma unroll
;     for (int i = 0; i < TI; i++)
; #pragma unroll
;       for (int j = 0; j < TJ; j++) acc[i][j] = mfma16(af[i], bfr[j], acc[i][j]);
;   }
.LBB0_1038:
	v_mov_b32_e32 v131, v195
	v_and_b32_e32 v143, 15, v131
	v_or_b32_e32 v144, v143, v141
	v_and_b32_e32 v148, 48, v131
	v_mul_u32_u24_e32 v131, 0x50, v144
	v_lshl_add_u32 v131, v131, 1, v148
	v_or_b32_e32 v143, v143, v142
	v_mad_u32_u24 v238, v143, s36, v148
	v_lshl_add_u64 v[132:133], v[132:133], 0, s[34:35]
	v_lshl_add_u64 v[134:135], v[134:135], 0, s[34:35]
	s_and_b64 vcc, exec, s[8:9]
	ds_read_b128 v[148:151], v131 offset:20480
	ds_read_b128 v[164:167], v238
	ds_read_b128 v[168:171], v238 offset:2560
	ds_read_b128 v[172:175], v238 offset:5120
	ds_read_b128 v[176:179], v238 offset:7680
	ds_read_b128 v[152:155], v131 offset:23040
	ds_read_b128 v[156:159], v131 offset:25600
	ds_read_b128 v[160:163], v131 offset:28160
	ds_read_b128 v[180:183], v238 offset:64
	ds_read_b128 v[184:187], v238 offset:2624
	s_waitcnt lgkmcnt(8)
	v_mfma_f32_16x16x32_bf16 v[114:117], v[148:151], v[164:167], v[114:117]
	s_waitcnt lgkmcnt(7)
	v_mfma_f32_16x16x32_bf16 v[126:129], v[148:151], v[168:171], v[126:129]
	s_waitcnt lgkmcnt(6)
	v_mfma_f32_16x16x32_bf16 v[122:125], v[148:151], v[172:175], v[122:125]
	s_waitcnt lgkmcnt(5)
	v_mfma_f32_16x16x32_bf16 v[118:121], v[148:151], v[176:179], v[118:121]
	ds_read_b128 v[148:151], v131 offset:20544
	s_waitcnt lgkmcnt(5)
	v_mfma_f32_16x16x32_bf16 v[110:113], v[152:155], v[164:167], v[110:113]
	v_mfma_f32_16x16x32_bf16 v[106:109], v[152:155], v[168:171], v[106:109]
	v_mfma_f32_16x16x32_bf16 v[102:105], v[152:155], v[172:175], v[102:105]
	v_mfma_f32_16x16x32_bf16 v[98:101], v[152:155], v[176:179], v[98:101]
	ds_read_b128 v[152:155], v131 offset:23104
	s_waitcnt lgkmcnt(5)
	v_mfma_f32_16x16x32_bf16 v[94:97], v[156:159], v[164:167], v[94:97]
	v_mfma_f32_16x16x32_bf16 v[82:85], v[156:159], v[168:171], v[82:85]
	v_mfma_f32_16x16x32_bf16 v[78:81], v[156:159], v[172:175], v[78:81]
	v_mfma_f32_16x16x32_bf16 v[70:73], v[156:159], v[176:179], v[70:73]
	ds_read_b128 v[156:159], v131 offset:25664
	s_waitcnt lgkmcnt(5)
	v_mfma_f32_16x16x32_bf16 v[66:69], v[160:163], v[172:175], v[66:69]
	v_mfma_f32_16x16x32_bf16 v[90:93], v[160:163], v[176:179], v[90:93]
	ds_read_b128 v[172:175], v238 offset:5184
	ds_read_b128 v[176:179], v238 offset:7744
	v_mfma_f32_16x16x32_bf16 v[86:89], v[160:163], v[164:167], v[86:89]
	v_mfma_f32_16x16x32_bf16 v[74:77], v[160:163], v[168:171], v[74:77]
	ds_read_b128 v[160:163], v131 offset:28224
	s_waitcnt lgkmcnt(5)
	v_mfma_f32_16x16x32_bf16 v[114:117], v[148:151], v[180:183], v[114:117]
	s_waitcnt lgkmcnt(4)
	v_mfma_f32_16x16x32_bf16 v[110:113], v[152:155], v[180:183], v[110:113]
	s_waitcnt lgkmcnt(3)
	v_mfma_f32_16x16x32_bf16 v[94:97], v[156:159], v[180:183], v[94:97]
	v_mfma_f32_16x16x32_bf16 v[126:129], v[148:151], v[184:187], v[126:129]
	v_mfma_f32_16x16x32_bf16 v[106:109], v[152:155], v[184:187], v[106:109]
	v_mfma_f32_16x16x32_bf16 v[82:85], v[156:159], v[184:187], v[82:85]
	s_waitcnt lgkmcnt(2)
	v_mfma_f32_16x16x32_bf16 v[122:125], v[148:151], v[172:175], v[122:125]
	v_mfma_f32_16x16x32_bf16 v[102:105], v[152:155], v[172:175], v[102:105]
	v_mfma_f32_16x16x32_bf16 v[78:81], v[156:159], v[172:175], v[78:81]
	s_waitcnt lgkmcnt(1)
	v_mfma_f32_16x16x32_bf16 v[118:121], v[148:151], v[176:179], v[118:121]
	v_mfma_f32_16x16x32_bf16 v[98:101], v[152:155], v[176:179], v[98:101]
	v_mfma_f32_16x16x32_bf16 v[70:73], v[156:159], v[176:179], v[70:73]
	s_waitcnt lgkmcnt(0)
	v_mfma_f32_16x16x32_bf16 v[86:89], v[160:163], v[180:183], v[86:89]
	v_mfma_f32_16x16x32_bf16 v[74:77], v[160:163], v[184:187], v[74:77]
	v_mfma_f32_16x16x32_bf16 v[66:69], v[160:163], v[172:175], v[66:69]
	v_mfma_f32_16x16x32_bf16 v[90:93], v[160:163], v[176:179], v[90:93]
	s_cbranch_vccnz .LBB0_1043

; DEV f32x4 mfma16(bf16x8 a, bf16x8 b, f32x4 c) { return __builtin_amdgcn_mfma_f32_16x16x32_bf16(a, b, c, 0, 0, 0); }
; #define G_LOAD(RA, RB, KT) { _Pragma("unroll") for (int i = 0; i < 4; i++) { \
;       RA[i] = *(const u32x4*)(Ap + (size_t)(i * 32) * lda + (KT) * 64); RB[i] = *(const u32x4*)(Bp + (size_t)(i * 32) * ldb + (KT) * 64); } }
; #define G_STORE(RA, RB) { _Pragma("unroll") for (int i = 0; i < 4; i++) { \
;       *(u32x4*)(As + (lrow + i * 32) * GLD + lcc * 8) = RA[i]; *(u32x4*)(Bs + (lrow + i * 32) * GLD + lcc * 8) = RB[i]; } }
; template <int TI, int TJ, int KS>
; DEV void mfma_lds(const bf16_t* Arows, int lda, const bf16_t* Brows, int ldb, int i0, int j0, f32x4 (&acc)[TI][TJ]) {
;     ...
;   for (int ks = 0; ks < KS; ks++) {
;     bf16x8 af[TI], bfr[TJ];
; #pragma unroll
;     for (int i = 0; i < TI; i++) af[i] = *(const bf16x8*)(Arows + (i0 + i * 16 + l15) * lda + ks * 32 + quad * 8);
; #pragma unroll
;     for (int j = 0; j < TJ; j++) bfr[j] = *(const bf16x8*)(Brows + (j0 + j * 16 + l15) * ldb + ks * 32 + quad * 8);
; #pragma unroll
;     for (int i = 0; i < TI; i++)
; #pragma unroll
;       for (int j = 0; j < TJ; j++) acc[i][j] = mfma16(af[i], bfr[j], acc[i][j]);
;   }
; template <class Epi>
; DEV void gemm_tile(const bf16_t* __restrict__ A, int lda, const bf16_t* __restrict__ Bt, int ldb, int K, int m0, int n0,
;                    Epi& epi, char* smem) {
;     ...
;   for (int kt = 0; kt < nk; kt += 2) {
;     __syncthreads();
;     G_STORE(ra0, rb0);
;     __syncthreads();
;     if (kt + 2 < nk) G_LOAD(ra0, rb0, kt + 2);
;     mfma_lds<4, 4, 2>(Bs, GLD, As, GLD, wn * 64, wm * 64, acc);
;     __syncthreads();
;     G_STORE(ra1, rb1);
;     __syncthreads();
;     if (kt + 3 < nk) G_LOAD(ra1, rb1, kt + 3);
;     mfma_lds<4, 4, 2>(Bs, GLD, As, GLD, wn * 64, wm * 64, acc);
;   }
.LBB0_1041:
	v_mov_b32_e32 v131, v195
	s_cmp_gt_u32 s14, 12
	v_and_b32_e32 v143, 15, v131
	v_or_b32_e32 v144, v143, v141
	v_and_b32_e32 v148, 48, v131
	v_mul_u32_u24_e32 v131, 0x50, v144
	v_lshl_add_u32 v131, v131, 1, v148
	v_or_b32_e32 v143, v143, v142
	v_mad_u32_u24 v238, v143, s36, v148
	ds_read_b128 v[148:151], v131 offset:20480
	ds_read_b128 v[164:167], v238
	ds_read_b128 v[168:171], v238 offset:2560
	ds_read_b128 v[172:175], v238 offset:5120
	ds_read_b128 v[176:179], v238 offset:7680
	ds_read_b128 v[152:155], v131 offset:23040
	ds_read_b128 v[156:159], v131 offset:25600
	ds_read_b128 v[160:163], v131 offset:28160
	ds_read_b128 v[180:183], v238 offset:64
	ds_read_b128 v[184:187], v238 offset:2624
	s_waitcnt lgkmcnt(8)
	v_mfma_f32_16x16x32_bf16 v[114:117], v[148:151], v[164:167], v[114:117]
	s_waitcnt lgkmcnt(7)
	v_mfma_f32_16x16x32_bf16 v[126:129], v[148:151], v[168:171], v[126:129]
	s_waitcnt lgkmcnt(6)
	v_mfma_f32_16x16x32_bf16 v[122:125], v[148:151], v[172:175], v[122:125]
	s_waitcnt lgkmcnt(5)
	v_mfma_f32_16x16x32_bf16 v[118:121], v[148:151], v[176:179], v[118:121]
	ds_read_b128 v[148:151], v131 offset:20544
	s_waitcnt lgkmcnt(5)
	v_mfma_f32_16x16x32_bf16 v[110:113], v[152:155], v[164:167], v[110:113]
	v_mfma_f32_16x16x32_bf16 v[106:109], v[152:155], v[168:171], v[106:109]
	v_mfma_f32_16x16x32_bf16 v[102:105], v[152:155], v[172:175], v[102:105]
	v_mfma_f32_16x16x32_bf16 v[98:101], v[152:155], v[176:179], v[98:101]
	ds_read_b128 v[152:155], v131 offset:23104
	s_waitcnt lgkmcnt(5)
	v_mfma_f32_16x16x32_bf16 v[94:97], v[156:159], v[164:167], v[94:97]
	v_mfma_f32_16x16x32_bf16 v[82:85], v[156:159], v[168:171], v[82:85]
	v_mfma_f32_16x16x32_bf16 v[78:81], v[156:159], v[172:175], v[78:81]
	v_mfma_f32_16x16x32_bf16 v[70:73], v[156:159], v[176:179], v[70:73]
	ds_read_b128 v[156:159], v131 offset:25664
	s_waitcnt lgkmcnt(5)
	v_mfma_f32_16x16x32_bf16 v[66:69], v[160:163], v[172:175], v[66:69]
	v_mfma_f32_16x16x32_bf16 v[90:93], v[160:163], v[176:179], v[90:93]
	ds_read_b128 v[172:175], v238 offset:5184
	ds_read_b128 v[176:179], v238 offset:7744
	v_mfma_f32_16x16x32_bf16 v[86:89], v[160:163], v[164:167], v[86:89]
	v_mfma_f32_16x16x32_bf16 v[74:77], v[160:163], v[168:171], v[74:77]
	ds_read_b128 v[160:163], v131 offset:28224
	s_waitcnt lgkmcnt(5)
	v_mfma_f32_16x16x32_bf16 v[114:117], v[148:151], v[180:183], v[114:117]
	s_waitcnt lgkmcnt(4)
	v_mfma_f32_16x16x32_bf16 v[110:113], v[152:155], v[180:183], v[110:113]
	s_waitcnt lgkmcnt(3)
	v_mfma_f32_16x16x32_bf16 v[94:97], v[156:159], v[180:183], v[94:97]
	v_mfma_f32_16x16x32_bf16 v[126:129], v[148:151], v[184:187], v[126:129]
	v_mfma_f32_16x16x32_bf16 v[106:109], v[152:155], v[184:187], v[106:109]
	v_mfma_f32_16x16x32_bf16 v[82:85], v[156:159], v[184:187], v[82:85]
	s_waitcnt lgkmcnt(2)
	v_mfma_f32_16x16x32_bf16 v[122:125], v[148:151], v[172:175], v[122:125]
	v_mfma_f32_16x16x32_bf16 v[102:105], v[152:155], v[172:175], v[102:105]
	v_mfma_f32_16x16x32_bf16 v[78:81], v[156:159], v[172:175], v[78:81]
	s_waitcnt lgkmcnt(1)
	v_mfma_f32_16x16x32_bf16 v[118:121], v[148:151], v[176:179], v[118:121]
	v_mfma_f32_16x16x32_bf16 v[98:101], v[152:155], v[176:179], v[98:101]
	v_mfma_f32_16x16x32_bf16 v[70:73], v[156:159], v[176:179], v[70:73]
	s_waitcnt lgkmcnt(0)
	v_mfma_f32_16x16x32_bf16 v[86:89], v[160:163], v[180:183], v[86:89]
	s_barrier
	v_mfma_f32_16x16x32_bf16 v[74:77], v[160:163], v[184:187], v[74:77]
	s_waitcnt vmcnt(8)
	ds_write_b128 v130, v[6:9]
	ds_write_b128 v130, v[14:17] offset:20480
	ds_write_b128 v130, v[22:25] offset:5120
	ds_write_b128 v130, v[30:33] offset:25600
	ds_write_b128 v130, v[38:41] offset:10240
	ds_write_b128 v130, v[46:49] offset:30720
	ds_write_b128 v130, v[54:57] offset:15360
	ds_write_b128 v130, v[62:65] offset:35840
	v_mfma_f32_16x16x32_bf16 v[66:69], v[160:163], v[172:175], v[66:69]
	s_waitcnt lgkmcnt(0)
	s_barrier
	v_mfma_f32_16x16x32_bf16 v[90:93], v[160:163], v[176:179], v[90:93]
	s_cbranch_scc1 .LBB0_1038
	v_add_co_u32_e32 v6, vcc, 0x4200000, v138
	s_nop 1
	v_addc_co_u32_e32 v7, vcc, 0, v139, vcc
	v_add_co_u32_e32 v14, vcc, 0xa300000, v136
	global_load_dwordx4 v[6:9], v[6:7], off offset:384
	s_nop 0
	v_addc_co_u32_e32 v15, vcc, 0, v137, vcc
	v_add_co_u32_e32 v22, vcc, 0x4211000, v138
	global_load_dwordx4 v[14:17], v[14:15], off offset:384
	s_nop 0
	v_addc_co_u32_e32 v23, vcc, 0, v139, vcc
	v_add_co_u32_e32 v30, vcc, 0xa311000, v136
	global_load_dwordx4 v[22:25], v[22:23], off offset:384
	s_nop 0
	v_addc_co_u32_e32 v31, vcc, 0, v137, vcc
	v_add_co_u32_e32 v38, vcc, 0x4222000, v138
	global_load_dwordx4 v[30:33], v[30:31], off offset:384
	s_nop 0
	v_addc_co_u32_e32 v39, vcc, 0, v139, vcc
	v_add_co_u32_e32 v46, vcc, 0xa322000, v136
	global_load_dwordx4 v[38:41], v[38:39], off offset:384
	s_nop 0
	v_addc_co_u32_e32 v47, vcc, 0, v137, vcc
	v_add_co_u32_e32 v54, vcc, 0x4233000, v138
	global_load_dwordx4 v[46:49], v[46:47], off offset:384
	s_nop 0
	v_addc_co_u32_e32 v55, vcc, 0, v139, vcc
	v_add_co_u32_e32 v62, vcc, 0xa333000, v136
	global_load_dwordx4 v[54:57], v[54:55], off offset:384
	s_nop 0
	v_addc_co_u32_e32 v63, vcc, 0, v137, vcc
	global_load_dwordx4 v[62:65], v[62:63], off offset:384
	s_branch .LBB0_1038

; DEV unsigned pack2(float a, float b) { f32x2 v = {a, b}; return __builtin_bit_cast(unsigned, __builtin_convertvector(v, bf2_t)); }
; template <class Epi>
; DEV void gemm_tile(const bf16_t* __restrict__ A, int lda, const bf16_t* __restrict__ Bt, int ldb, int K, int m0, int n0,
;                    Epi& epi, char* smem) {
;     ...
; #pragma unroll
;   for (int i = 0; i < 4; i++)
; #pragma unroll
;     for (int j = 0; j < 4; j++) epi(m0 + wm * 64 + j * 16 + l15, n0 + wn * 64 + i * 16 + quad * 4, acc[i][j]);
;   DEV void operator()(int m, int n, f32x4 v) {
;     if (n < 1440) { uint2 r; r.x = pack2(v[0], v[1]); r.y = pack2(v[2], v[3]); *(uint2*)(P0 + (size_t)m * 1536 + n) = r; }
;   }
.LBB0_1043:
	s_nop 7
	s_nop 7
	v_lshrrev_b32_e32 v0, 2, v140
	v_and_b32_e32 v0, 12, v0
	v_or3_b32 v2, s13, v0, v141
	v_and_or_b32 v0, v140, 15, s12
	s_waitcnt vmcnt(7)
	v_add_u32_e32 v8, v0, v142
	s_movk_i32 s8, 0x5a0
	v_cmp_gt_i32_e32 vcc, s8, v2
	v_or_b32_e32 v7, 16, v8
	v_or_b32_e32 v6, 32, v8
	v_or_b32_e32 v0, 48, v8
	s_and_saveexec_b64 s[8:9], vcc
	s_cbranch_execz .LBB0_1045
	v_ashrrev_i32_e32 v3, 31, v2
	v_lshl_add_u64 v[4:5], v[2:3], 1, s[0:1]
	s_movk_i32 s14, 0xc00
	v_cvt_pk_bf16_f32 v10, v114, v115
	v_cvt_pk_bf16_f32 v11, v116, v117
	v_mad_i64_i32 v[12:13], s[12:13], v8, s14, v[4:5]
	global_store_dwordx2 v[12:13], v[10:11], off
	v_cvt_pk_bf16_f32 v10, v126, v127
	v_cvt_pk_bf16_f32 v11, v128, v129
	v_mad_i64_i32 v[12:13], s[12:13], v7, s14, v[4:5]
	global_store_dwordx2 v[12:13], v[10:11], off
	v_cvt_pk_bf16_f32 v10, v122, v123
	v_cvt_pk_bf16_f32 v11, v124, v125
	v_mad_i64_i32 v[12:13], s[12:13], v6, s14, v[4:5]
	global_store_dwordx2 v[12:13], v[10:11], off
	v_cvt_pk_bf16_f32 v10, v118, v119
	v_cvt_pk_bf16_f32 v11, v120, v121
	v_mad_i64_i32 v[4:5], s[12:13], v0, s14, v[4:5]
	global_store_dwordx2 v[4:5], v[10:11], off
